# EPI4+EPI6: second-half gate/bias vectors of two GEMM epilogues requested with the first half (counted waits, no store drain); conv is_ctx mask recomputed instead of lane-parked
# baseline (speedup 1.0000x reference)
; #define PG8_STAGE(bufoff, gbase, voff) do { _Pragma("unroll") for (int _i = 0; _i < 2; ++_i) \
;         __builtin_amdgcn_global_load_lds((const unsigned*)((const char*)(gbase) + (voff)[_i]), (PG8_LAS unsigned*)(lds + (bufoff) + ldsw + _i * 8192), 16, 0, 0); } while (0)
; #define PG8_LDA(dst, b, h) do { _Pragma("unroll") for (int m = 0; m < 4; ++m) _Pragma("unroll") for (int k = 0; k < 2; ++k) dst[m][k] = *(const PG8_LAS bf16x8*)(lds + PG8_SA(b, h) + aoff + m * 2048 + k * 1024); } while (0)
; #define PG8_LDB(dst, b, h) do { _Pragma("unroll") for (int n = 0; n < 2; ++n) _Pragma("unroll") for (int k = 0; k < 2; ++k) dst[n][k] = *(const PG8_LAS bf16x8*)(lds + PG8_SB(b, h) + boff + n * 2048 + k * 1024); } while (0)
; #define PG8_MMA(ai, bj, At, Bt) do { __builtin_amdgcn_s_setprio(1); _Pragma("unroll") for (int m = 0; m < 4; ++m) _Pragma("unroll") for (int n = 0; n < 2; ++n) _Pragma("unroll") for (int k = 0; k < 2; ++k) \
;         acc[ai][bj][m][n] = __builtin_amdgcn_mfma_f32_16x16x32_bf16(Bt[n][k], At[m][k], acc[ai][bj][m][n], 0, 0, 0); __builtin_amdgcn_s_setprio(0); } while (0)
; #define PG8_WAIT_L(n) asm volatile("s_waitcnt lgkmcnt(" #n ")" ::: "memory")
; #define PG8_BAR __builtin_amdgcn_s_barrier()
; #define PG8_SCHED __builtin_amdgcn_sched_barrier(0)
; template <class Epi, class Sched>
; __device__ __forceinline__ void gemm_phase(PG8_LAS unsigned char* lds, const Gemm g, const Sched& S, const Epi& E, int tid_in) {
;     ...
;             PG8_LDB(B0, 0, 0); PG8_SCHED; PG8_LDA(At, 0, 0); PG8_STAGE(PG8_SA(1, 1), a1 + hstep, voffA);
;             PG8_WAIT_L(8); PG8_BAR; PG8_WAIT_L(0); PG8_MMA(0, 0, At, B0); PG8_BAR; PG8_SCHED;
;             PG8_LDB(B1, 0, 1); PG8_STAGE(PG8_SB(0, 0), b2, voffB);
;             PG8_BAR; PG8_WAIT_L(0); PG8_MMA(0, 1, At, B1); PG8_BAR;
;             PG8_LDA(At, 0, 1); PG8_STAGE(PG8_SA(0, 0), a2, voffA);
;             PG8_BAR; PG8_WAIT_L(0); PG8_MMA(1, 0, At, B0); PG8_BAR; PG8_SCHED;
.LBB0_350:
	s_add_u32 s20, s18, 0xfff80080
	s_addc_u32 s21, s19, -1
	s_add_i32 s46, 0, 0x10000
	v_add_u32_e32 v146, s46, v171
	ds_read_b128 v[134:137], v146
	ds_read_b128 v[138:141], v146 offset:1024
	ds_read_b128 v[142:145], v146 offset:2048
	ds_read_b128 v[146:149], v146 offset:3072
	s_cmp_eq_u32 s45, 28
	s_cselect_b32 s23, s11, s21
	s_cselect_b32 s22, s41, s20
	s_cselect_b32 s21, s9, s44
	s_cselect_b32 s20, s42, s43
	v_lshl_add_u64 v[186:187], s[18:19], 0, v[130:131]
	s_add_i32 m0, s17, 0xc000
	ds_read_b128 v[150:153], v173
	ds_read_b128 v[154:157], v173 offset:1024
	ds_read_b128 v[158:161], v173 offset:2048
	ds_read_b128 v[162:165], v173 offset:3072
	ds_read_b128 v[166:169], v173 offset:4096
	ds_read_b128 v[174:177], v173 offset:5120
	ds_read_b128 v[178:181], v173 offset:6144
	ds_read_b128 v[182:185], v173 offset:7168
	global_load_lds_dwordx4 v[186:187], off
	v_lshl_add_u64 v[186:187], s[18:19], 0, v[132:133]
	s_add_i32 m0, s17, 0xe000
	s_nop 0
	global_load_lds_dwordx4 v[186:187], off
	s_waitcnt lgkmcnt(8)
	s_barrier
	s_waitcnt lgkmcnt(0)
	s_setprio 1
	s_waitcnt lgkmcnt(0)
	v_mfma_f32_16x16x32_bf16 v[124:127], v[134:137], v[150:153], v[124:127]
	v_mfma_f32_16x16x32_bf16 v[120:123], v[142:145], v[150:153], v[120:123]
	v_mfma_f32_16x16x32_bf16 v[108:111], v[134:137], v[158:161], v[108:111]
	v_mfma_f32_16x16x32_bf16 v[104:107], v[142:145], v[158:161], v[104:107]
	v_mfma_f32_16x16x32_bf16 v[96:99], v[134:137], v[166:169], v[96:99]
	v_mfma_f32_16x16x32_bf16 v[88:91], v[142:145], v[166:169], v[88:91]
	v_mfma_f32_16x16x32_bf16 v[80:83], v[134:137], v[178:181], v[80:83]
	v_mfma_f32_16x16x32_bf16 v[72:75], v[142:145], v[178:181], v[72:75]
	v_mfma_f32_16x16x32_bf16 v[124:127], v[138:141], v[154:157], v[124:127]
	v_mfma_f32_16x16x32_bf16 v[120:123], v[146:149], v[154:157], v[120:123]
	v_mfma_f32_16x16x32_bf16 v[108:111], v[138:141], v[162:165], v[108:111]
	v_mfma_f32_16x16x32_bf16 v[104:107], v[146:149], v[162:165], v[104:107]
	v_mfma_f32_16x16x32_bf16 v[96:99], v[138:141], v[174:177], v[96:99]
	v_mfma_f32_16x16x32_bf16 v[88:91], v[146:149], v[174:177], v[88:91]
	v_mfma_f32_16x16x32_bf16 v[80:83], v[138:141], v[182:185], v[80:83]
	v_mfma_f32_16x16x32_bf16 v[72:75], v[146:149], v[182:185], v[72:75]
	s_setprio 0
	s_barrier
	s_add_i32 s50, 0, 0x14000
	v_add_u32_e32 v190, s50, v171
	s_add_i32 s46, s46, s30
	ds_read_b128 v[186:189], v190
	ds_read_b128 v[194:197], v190 offset:1024
	ds_read_b128 v[200:203], v190 offset:2048
	ds_read_b128 v[204:207], v190 offset:3072
	v_lshl_add_u64 v[190:191], s[20:21], 0, v[192:193]
	s_mov_b32 m0, s46
	v_lshl_add_u64 v[208:209], s[20:21], 0, v[128:129]
	global_load_lds_dwordx4 v[190:191], off
	s_add_i32 m0, s46, 0x2000
	s_nop 0
	global_load_lds_dwordx4 v[208:209], off
	s_barrier
	s_waitcnt lgkmcnt(0)
	s_setprio 1
	s_waitcnt lgkmcnt(0)
	v_mfma_f32_16x16x32_bf16 v[116:119], v[186:189], v[150:153], v[116:119]
	v_mfma_f32_16x16x32_bf16 v[112:115], v[200:203], v[150:153], v[112:115]
	v_mfma_f32_16x16x32_bf16 v[100:103], v[186:189], v[158:161], v[100:103]
	v_mfma_f32_16x16x32_bf16 v[92:95], v[200:203], v[158:161], v[92:95]
	v_mfma_f32_16x16x32_bf16 v[84:87], v[186:189], v[166:169], v[84:87]
	v_mfma_f32_16x16x32_bf16 v[76:79], v[200:203], v[166:169], v[76:79]
	v_mfma_f32_16x16x32_bf16 v[68:71], v[186:189], v[178:181], v[68:71]
	v_mfma_f32_16x16x32_bf16 v[64:67], v[200:203], v[178:181], v[64:67]
	v_mfma_f32_16x16x32_bf16 v[116:119], v[194:197], v[154:157], v[116:119]
	v_mfma_f32_16x16x32_bf16 v[112:115], v[204:207], v[154:157], v[112:115]
	v_mfma_f32_16x16x32_bf16 v[100:103], v[194:197], v[162:165], v[100:103]
	v_mfma_f32_16x16x32_bf16 v[92:95], v[204:207], v[162:165], v[92:95]
	v_mfma_f32_16x16x32_bf16 v[84:87], v[194:197], v[174:177], v[84:87]
	v_mfma_f32_16x16x32_bf16 v[76:79], v[204:207], v[174:177], v[76:79]
	v_mfma_f32_16x16x32_bf16 v[68:71], v[194:197], v[182:185], v[68:71]
	v_mfma_f32_16x16x32_bf16 v[64:67], v[204:207], v[182:185], v[64:67]
	s_setprio 0
	s_mov_b32 m0, s17
	v_lshl_add_u64 v[210:211], s[22:23], 0, v[192:193]
	s_barrier
	ds_read_b128 v[150:153], v173 offset:16384
	ds_read_b128 v[154:157], v173 offset:17408
	ds_read_b128 v[158:161], v173 offset:18432
	ds_read_b128 v[162:165], v173 offset:19456
	ds_read_b128 v[166:169], v173 offset:20480
	ds_read_b128 v[174:177], v173 offset:21504
	ds_read_b128 v[178:181], v173 offset:22528
	ds_read_b128 v[182:185], v173 offset:23552
	global_load_lds_dwordx4 v[210:211], off
	v_lshl_add_u64 v[212:213], s[22:23], 0, v[128:129]
	s_mov_b32 m0, s31
	s_nop 0
	global_load_lds_dwordx4 v[212:213], off
	s_barrier
	s_waitcnt lgkmcnt(0)
	s_setprio 1
	s_waitcnt lgkmcnt(0)
	v_mfma_f32_16x16x32_bf16 v[60:63], v[134:137], v[150:153], v[60:63]
	v_mfma_f32_16x16x32_bf16 v[56:59], v[142:145], v[150:153], v[56:59]
	v_mfma_f32_16x16x32_bf16 v[48:51], v[134:137], v[158:161], v[48:51]
	v_mfma_f32_16x16x32_bf16 v[40:43], v[142:145], v[158:161], v[40:43]
	v_mfma_f32_16x16x32_bf16 v[32:35], v[134:137], v[166:169], v[32:35]
	v_mfma_f32_16x16x32_bf16 v[24:27], v[142:145], v[166:169], v[24:27]
	v_mfma_f32_16x16x32_bf16 v[16:19], v[134:137], v[178:181], v[16:19]
	v_mfma_f32_16x16x32_bf16 v[8:11], v[142:145], v[178:181], v[8:11]
	v_mfma_f32_16x16x32_bf16 v[60:63], v[138:141], v[154:157], v[60:63]
	v_mfma_f32_16x16x32_bf16 v[56:59], v[146:149], v[154:157], v[56:59]
	v_mfma_f32_16x16x32_bf16 v[48:51], v[138:141], v[162:165], v[48:51]
	v_mfma_f32_16x16x32_bf16 v[40:43], v[146:149], v[162:165], v[40:43]
	v_mfma_f32_16x16x32_bf16 v[32:35], v[138:141], v[174:177], v[32:35]
	v_mfma_f32_16x16x32_bf16 v[24:27], v[146:149], v[174:177], v[24:27]
	v_mfma_f32_16x16x32_bf16 v[16:19], v[138:141], v[182:185], v[16:19]
	v_mfma_f32_16x16x32_bf16 v[8:11], v[146:149], v[182:185], v[8:11]
	s_setprio 0
	s_barrier
; #define PG8_STAGE(bufoff, gbase, voff) do { _Pragma("unroll") for (int _i = 0; _i < 2; ++_i) \
;         __builtin_amdgcn_global_load_lds((const unsigned*)((const char*)(gbase) + (voff)[_i]), (PG8_LAS unsigned*)(lds + (bufoff) + ldsw + _i * 8192), 16, 0, 0); } while (0)
; #define PG8_LDA(dst, b, h) do { _Pragma("unroll") for (int m = 0; m < 4; ++m) _Pragma("unroll") for (int k = 0; k < 2; ++k) dst[m][k] = *(const PG8_LAS bf16x8*)(lds + PG8_SA(b, h) + aoff + m * 2048 + k * 1024); } while (0)
; #define PG8_LDB(dst, b, h) do { _Pragma("unroll") for (int n = 0; n < 2; ++n) _Pragma("unroll") for (int k = 0; k < 2; ++k) dst[n][k] = *(const PG8_LAS bf16x8*)(lds + PG8_SB(b, h) + boff + n * 2048 + k * 1024); } while (0)
; #define PG8_MMA(ai, bj, At, Bt) do { __builtin_amdgcn_s_setprio(1); _Pragma("unroll") for (int m = 0; m < 4; ++m) _Pragma("unroll") for (int n = 0; n < 2; ++n) _Pragma("unroll") for (int k = 0; k < 2; ++k) \
;         acc[ai][bj][m][n] = __builtin_amdgcn_mfma_f32_16x16x32_bf16(Bt[n][k], At[m][k], acc[ai][bj][m][n], 0, 0, 0); __builtin_amdgcn_s_setprio(0); } while (0)
; #define PG8_WAIT_V(n) asm volatile("s_waitcnt vmcnt(" #n ")" ::: "memory")
; #define PG8_WAIT_L(n) asm volatile("s_waitcnt lgkmcnt(" #n ")" ::: "memory")
; #define PG8_BAR __builtin_amdgcn_s_barrier()
; #define PG8_SCHED __builtin_amdgcn_sched_barrier(0)
; template <class Epi, class Sched>
; __device__ __forceinline__ void gemm_phase(PG8_LAS unsigned char* lds, const Gemm g, const Sched& S, const Epi& E, int tid_in) {
;     ...
;             PG8_STAGE(PG8_SB(0, 1), b2 + hstep, voffB);
;             PG8_WAIT_V(6); PG8_BAR; PG8_MMA(1, 1, At, B1); PG8_BAR;
;             PG8_LDB(B0, 1, 0); PG8_SCHED; PG8_LDA(At, 1, 0); PG8_STAGE(PG8_SA(0, 1), a2 + hstep, voffA);
;             PG8_WAIT_L(8); PG8_BAR; PG8_WAIT_L(0); PG8_MMA(0, 0, At, B0); PG8_BAR; PG8_SCHED;
;             PG8_LDB(B1, 1, 1); PG8_STAGE(PG8_SB(1, 0), b3, voffB);
;             PG8_BAR; PG8_WAIT_L(0); PG8_MMA(0, 1, At, B1); PG8_BAR;
;             PG8_LDA(At, 1, 1); PG8_STAGE(PG8_SA(1, 0), a3, voffA);
	s_add_u32 s48, s20, 0x80000
	s_addc_u32 s49, s21, 0
	s_add_i32 s46, s50, s30
	v_lshl_add_u64 v[134:135], s[48:49], 0, v[192:193]
	s_mov_b32 m0, s46
	s_nop 0
	global_load_lds_dwordx4 v[134:135], off
	v_lshl_add_u64 v[134:135], s[48:49], 0, v[128:129]
	s_add_i32 m0, s46, 0x2000
	s_nop 0
	global_load_lds_dwordx4 v[134:135], off
	s_waitcnt vmcnt(6)
	s_barrier
	s_setprio 1
	v_mfma_f32_16x16x32_bf16 v[52:55], v[186:189], v[150:153], v[52:55]
	v_mfma_f32_16x16x32_bf16 v[44:47], v[200:203], v[150:153], v[44:47]
	v_mfma_f32_16x16x32_bf16 v[36:39], v[186:189], v[158:161], v[36:39]
	v_mfma_f32_16x16x32_bf16 v[28:31], v[200:203], v[158:161], v[28:31]
	v_mfma_f32_16x16x32_bf16 v[20:23], v[186:189], v[166:169], v[20:23]
	v_mfma_f32_16x16x32_bf16 v[12:15], v[200:203], v[166:169], v[12:15]
	v_mfma_f32_16x16x32_bf16 v[4:7], v[186:189], v[178:181], v[4:7]
	v_mfma_f32_16x16x32_bf16 v[0:3], v[200:203], v[178:181], v[0:3]
	v_mfma_f32_16x16x32_bf16 v[52:55], v[194:197], v[154:157], v[52:55]
	v_mfma_f32_16x16x32_bf16 v[44:47], v[204:207], v[154:157], v[44:47]
	v_mfma_f32_16x16x32_bf16 v[36:39], v[194:197], v[162:165], v[36:39]
	v_mfma_f32_16x16x32_bf16 v[28:31], v[204:207], v[162:165], v[28:31]
	v_mfma_f32_16x16x32_bf16 v[20:23], v[194:197], v[174:177], v[20:23]
	v_mfma_f32_16x16x32_bf16 v[12:15], v[204:207], v[174:177], v[12:15]
	v_mfma_f32_16x16x32_bf16 v[4:7], v[194:197], v[182:185], v[4:7]
	v_mfma_f32_16x16x32_bf16 v[0:3], v[204:207], v[182:185], v[0:3]
	s_setprio 0
	s_add_i32 s46, 0, 0x18000
	v_add_u32_e32 v146, s46, v171
	s_barrier
	ds_read_b128 v[134:137], v146
	ds_read_b128 v[138:141], v146 offset:1024
	ds_read_b128 v[142:145], v146 offset:2048
	ds_read_b128 v[146:149], v146 offset:3072
	s_add_u32 s22, s22, 0x80000
	s_addc_u32 s23, s23, 0
	s_mov_b32 m0, s36
	v_lshl_add_u64 v[186:187], s[22:23], 0, v[192:193]
	ds_read_b128 v[150:153], v173 offset:32768
	ds_read_b128 v[154:157], v173 offset:33792
	ds_read_b128 v[158:161], v173 offset:34816
	ds_read_b128 v[162:165], v173 offset:35840
	ds_read_b128 v[166:169], v173 offset:36864
	ds_read_b128 v[174:177], v173 offset:37888
	ds_read_b128 v[178:181], v173 offset:38912
	ds_read_b128 v[182:185], v173 offset:39936
	global_load_lds_dwordx4 v[186:187], off
	v_lshl_add_u64 v[186:187], s[22:23], 0, v[128:129]
	s_mov_b32 m0, s37
	s_nop 0
	global_load_lds_dwordx4 v[186:187], off
	s_waitcnt lgkmcnt(8)
	s_barrier
	s_waitcnt lgkmcnt(0)
	s_setprio 1
	s_waitcnt lgkmcnt(0)
	v_mfma_f32_16x16x32_bf16 v[124:127], v[134:137], v[150:153], v[124:127]
	v_mfma_f32_16x16x32_bf16 v[120:123], v[142:145], v[150:153], v[120:123]
	v_mfma_f32_16x16x32_bf16 v[108:111], v[134:137], v[158:161], v[108:111]
	v_mfma_f32_16x16x32_bf16 v[104:107], v[142:145], v[158:161], v[104:107]
	v_mfma_f32_16x16x32_bf16 v[96:99], v[134:137], v[166:169], v[96:99]
	v_mfma_f32_16x16x32_bf16 v[88:91], v[142:145], v[166:169], v[88:91]
	v_mfma_f32_16x16x32_bf16 v[80:83], v[134:137], v[178:181], v[80:83]
	v_mfma_f32_16x16x32_bf16 v[72:75], v[142:145], v[178:181], v[72:75]
	v_mfma_f32_16x16x32_bf16 v[124:127], v[138:141], v[154:157], v[124:127]
	v_mfma_f32_16x16x32_bf16 v[120:123], v[146:149], v[154:157], v[120:123]
	v_mfma_f32_16x16x32_bf16 v[108:111], v[138:141], v[162:165], v[108:111]
	v_mfma_f32_16x16x32_bf16 v[104:107], v[146:149], v[162:165], v[104:107]
	v_mfma_f32_16x16x32_bf16 v[96:99], v[138:141], v[174:177], v[96:99]
	v_mfma_f32_16x16x32_bf16 v[88:91], v[146:149], v[174:177], v[88:91]
	v_mfma_f32_16x16x32_bf16 v[80:83], v[138:141], v[182:185], v[80:83]
	v_mfma_f32_16x16x32_bf16 v[72:75], v[146:149], v[182:185], v[72:75]
	s_setprio 0
	s_barrier
	s_add_i32 s22, 0, 0x1c000
	s_add_i32 s23, s46, s30
	v_add_u32_e32 v199, s22, v171
	v_lshl_add_u64 v[190:191], v[190:191], 0, s[74:75]
	s_mov_b32 m0, s23
	ds_read_b128 v[186:189], v199
	ds_read_b128 v[194:197], v199 offset:1024
	ds_read_b128 v[200:203], v199 offset:2048
	ds_read_b128 v[204:207], v199 offset:3072
	global_load_lds_dwordx4 v[190:191], off
	v_lshl_add_u64 v[190:191], v[208:209], 0, s[74:75]
	s_add_i32 m0, s23, 0x2000
	s_nop 0
	global_load_lds_dwordx4 v[190:191], off
	s_barrier
	s_waitcnt lgkmcnt(0)
	s_setprio 1
	s_waitcnt lgkmcnt(0)
	v_mfma_f32_16x16x32_bf16 v[116:119], v[186:189], v[150:153], v[116:119]
	v_mfma_f32_16x16x32_bf16 v[112:115], v[200:203], v[150:153], v[112:115]
	v_mfma_f32_16x16x32_bf16 v[100:103], v[186:189], v[158:161], v[100:103]
	v_mfma_f32_16x16x32_bf16 v[92:95], v[200:203], v[158:161], v[92:95]
	v_mfma_f32_16x16x32_bf16 v[84:87], v[186:189], v[166:169], v[84:87]
	v_mfma_f32_16x16x32_bf16 v[76:79], v[200:203], v[166:169], v[76:79]
	v_mfma_f32_16x16x32_bf16 v[68:71], v[186:189], v[178:181], v[68:71]
	v_mfma_f32_16x16x32_bf16 v[64:67], v[200:203], v[178:181], v[64:67]
	v_mfma_f32_16x16x32_bf16 v[116:119], v[194:197], v[154:157], v[116:119]
	v_mfma_f32_16x16x32_bf16 v[112:115], v[204:207], v[154:157], v[112:115]
	v_mfma_f32_16x16x32_bf16 v[100:103], v[194:197], v[162:165], v[100:103]
	v_mfma_f32_16x16x32_bf16 v[92:95], v[204:207], v[162:165], v[92:95]
	v_mfma_f32_16x16x32_bf16 v[84:87], v[194:197], v[174:177], v[84:87]
	v_mfma_f32_16x16x32_bf16 v[76:79], v[204:207], v[174:177], v[76:79]
	v_mfma_f32_16x16x32_bf16 v[68:71], v[194:197], v[182:185], v[68:71]
	v_mfma_f32_16x16x32_bf16 v[64:67], v[204:207], v[182:185], v[64:67]
	s_setprio 0
	s_mov_b32 m0, s38
	v_lshl_add_u64 v[190:191], v[210:211], 0, s[74:75]
	s_barrier
	ds_read_b128 v[150:153], v173 offset:49152
	ds_read_b128 v[154:157], v173 offset:50176
	ds_read_b128 v[158:161], v173 offset:51200
	ds_read_b128 v[162:165], v173 offset:52224
	ds_read_b128 v[166:169], v173 offset:53248
	ds_read_b128 v[174:177], v173 offset:54272
	ds_read_b128 v[178:181], v173 offset:55296
	ds_read_b128 v[182:185], v173 offset:56320
	global_load_lds_dwordx4 v[190:191], off
	v_lshl_add_u64 v[190:191], v[212:213], 0, s[74:75]
	s_mov_b32 m0, s39
	s_nop 0
	global_load_lds_dwordx4 v[190:191], off
	s_barrier
; #define PG8_STAGE(bufoff, gbase, voff) do { _Pragma("unroll") for (int _i = 0; _i < 2; ++_i) \
;         __builtin_amdgcn_global_load_lds((const unsigned*)((const char*)(gbase) + (voff)[_i]), (PG8_LAS unsigned*)(lds + (bufoff) + ldsw + _i * 8192), 16, 0, 0); } while (0)
; #define PG8_LDA(dst, b, h) do { _Pragma("unroll") for (int m = 0; m < 4; ++m) _Pragma("unroll") for (int k = 0; k < 2; ++k) dst[m][k] = *(const PG8_LAS bf16x8*)(lds + PG8_SA(b, h) + aoff + m * 2048 + k * 1024); } while (0)
; #define PG8_MMA(ai, bj, At, Bt) do { __builtin_amdgcn_s_setprio(1); _Pragma("unroll") for (int m = 0; m < 4; ++m) _Pragma("unroll") for (int n = 0; n < 2; ++n) _Pragma("unroll") for (int k = 0; k < 2; ++k) \
;         acc[ai][bj][m][n] = __builtin_amdgcn_mfma_f32_16x16x32_bf16(Bt[n][k], At[m][k], acc[ai][bj][m][n], 0, 0, 0); __builtin_amdgcn_s_setprio(0); } while (0)
; #define PG8_WAIT_V(n) asm volatile("s_waitcnt vmcnt(" #n ")" ::: "memory")
; #define PG8_WAIT_L(n) asm volatile("s_waitcnt lgkmcnt(" #n ")" ::: "memory")
; #define PG8_BAR __builtin_amdgcn_s_barrier()
; #define PG8_SCHED __builtin_amdgcn_sched_barrier(0)
; template <class Epi, class Sched>
; __device__ __forceinline__ void gemm_phase(PG8_LAS unsigned char* lds, const Gemm g, const Sched& S, const Epi& E, int tid_in) {
;     ...
;             PG8_LDA(At, 1, 1); PG8_STAGE(PG8_SA(1, 0), a3, voffA);
;             PG8_BAR; PG8_WAIT_L(0); PG8_MMA(1, 0, At, B0); PG8_BAR; PG8_SCHED;
;             PG8_STAGE(PG8_SB(1, 1), b3 + hstep, voffB);
;             PG8_WAIT_V(6); PG8_BAR; PG8_MMA(1, 1, At, B1); PG8_BAR;
;     __device__ __forceinline__ void operator()(f32x4 (&acc)[2][2][4][2], const Unit& u, int wr, int wc, int fr, int fq) const {
;     ...
;             u32x2 gw[4][2][2];
; #pragma unroll
;             for (int m = 0; m < 4; ++m)
; #pragma unroll
;                 for (int bj = 0; bj < 2; ++bj)
; #pragma unroll
;                     for (int n = 0; n < 2; ++n) gw[m][bj][n] = *(const u32x2*)(gates + (size_t)(row0 + ai * 128 + m * 16) * 2048 + col0 + bj * 128 + n * 16);
	s_waitcnt lgkmcnt(0)
	s_setprio 1
	s_waitcnt lgkmcnt(0)
	v_mfma_f32_16x16x32_bf16 v[60:63], v[134:137], v[150:153], v[60:63]
	v_mfma_f32_16x16x32_bf16 v[56:59], v[142:145], v[150:153], v[56:59]
	v_mfma_f32_16x16x32_bf16 v[48:51], v[134:137], v[158:161], v[48:51]
	v_mfma_f32_16x16x32_bf16 v[40:43], v[142:145], v[158:161], v[40:43]
	v_mfma_f32_16x16x32_bf16 v[32:35], v[134:137], v[166:169], v[32:35]
	v_mfma_f32_16x16x32_bf16 v[24:27], v[142:145], v[166:169], v[24:27]
	v_mfma_f32_16x16x32_bf16 v[16:19], v[134:137], v[178:181], v[16:19]
	v_mfma_f32_16x16x32_bf16 v[8:11], v[142:145], v[178:181], v[8:11]
	v_mfma_f32_16x16x32_bf16 v[60:63], v[138:141], v[154:157], v[60:63]
	v_mfma_f32_16x16x32_bf16 v[56:59], v[146:149], v[154:157], v[56:59]
	v_mfma_f32_16x16x32_bf16 v[48:51], v[138:141], v[162:165], v[48:51]
	v_mfma_f32_16x16x32_bf16 v[40:43], v[146:149], v[162:165], v[40:43]
	v_mfma_f32_16x16x32_bf16 v[32:35], v[138:141], v[174:177], v[32:35]
	v_mfma_f32_16x16x32_bf16 v[24:27], v[146:149], v[174:177], v[24:27]
	v_mfma_f32_16x16x32_bf16 v[16:19], v[138:141], v[182:185], v[16:19]
	v_mfma_f32_16x16x32_bf16 v[8:11], v[146:149], v[182:185], v[8:11]
	s_setprio 0
	s_barrier
	s_add_u32 s20, s20, 0x80080
	s_addc_u32 s21, s21, 0
	s_add_i32 s22, s22, s30
	v_lshl_add_u64 v[134:135], s[20:21], 0, v[192:193]
	s_mov_b32 m0, s22
	s_nop 0
	global_load_lds_dwordx4 v[134:135], off
	v_lshl_add_u64 v[134:135], s[20:21], 0, v[128:129]
	s_add_i32 m0, s22, 0x2000
	s_nop 0
	global_load_lds_dwordx4 v[134:135], off
	s_waitcnt vmcnt(6)
	s_barrier
	s_setprio 1
	v_mfma_f32_16x16x32_bf16 v[52:55], v[186:189], v[150:153], v[52:55]
	v_mfma_f32_16x16x32_bf16 v[44:47], v[200:203], v[150:153], v[44:47]
	v_mfma_f32_16x16x32_bf16 v[36:39], v[186:189], v[158:161], v[36:39]
	v_mfma_f32_16x16x32_bf16 v[28:31], v[200:203], v[158:161], v[28:31]
	v_mfma_f32_16x16x32_bf16 v[20:23], v[186:189], v[166:169], v[20:23]
	v_mfma_f32_16x16x32_bf16 v[12:15], v[200:203], v[166:169], v[12:15]
	v_mfma_f32_16x16x32_bf16 v[4:7], v[186:189], v[178:181], v[4:7]
	v_mfma_f32_16x16x32_bf16 v[0:3], v[200:203], v[178:181], v[0:3]
	v_mfma_f32_16x16x32_bf16 v[52:55], v[194:197], v[154:157], v[52:55]
	v_mfma_f32_16x16x32_bf16 v[44:47], v[204:207], v[154:157], v[44:47]
	v_mfma_f32_16x16x32_bf16 v[36:39], v[194:197], v[162:165], v[36:39]
	v_mfma_f32_16x16x32_bf16 v[28:31], v[204:207], v[162:165], v[28:31]
	v_mfma_f32_16x16x32_bf16 v[20:23], v[194:197], v[174:177], v[20:23]
	v_mfma_f32_16x16x32_bf16 v[12:15], v[204:207], v[174:177], v[12:15]
	v_mfma_f32_16x16x32_bf16 v[4:7], v[194:197], v[182:185], v[4:7]
	v_mfma_f32_16x16x32_bf16 v[0:3], v[204:207], v[182:185], v[0:3]
	s_setprio 0
	s_add_i32 s45, s45, 2
	s_add_u32 s18, s18, 0x100
	s_addc_u32 s19, s19, 0
	s_add_u32 s43, s43, 0x100
	s_addc_u32 s44, s44, 0
	s_cmp_gt_u32 s45, 29
	s_barrier
	s_cbranch_scc0 .LBB0_350
	v_lshl_or_b32 v134, s33, 8, v172
	v_lshl_add_u32 v136, s16, 8, v170
	v_ashrrev_i32_e32 v135, 31, v134
	v_lshlrev_b64 v[134:135], 1, v[134:135]
	v_ashrrev_i32_e32 v137, 31, v136
	v_lshl_add_u64 v[138:139], s[0:1], 0, v[134:135]
	v_lshlrev_b64 v[140:141], 12, v[136:137]
	v_lshl_add_u64 v[140:141], v[138:139], 0, v[140:141]
	global_load_dwordx2 v[174:175], v[140:141], off
	global_load_dwordx2 v[176:177], v[140:141], off offset:32
	global_load_dwordx2 v[178:179], v[140:141], off offset:256
	global_load_dwordx2 v[180:181], v[140:141], off offset:288
	v_or_b32_e32 v166, 16, v136
	v_ashrrev_i32_e32 v167, 31, v166
	v_lshlrev_b64 v[140:141], 12, v[166:167]
	v_lshl_add_u64 v[140:141], v[138:139], 0, v[140:141]
	global_load_dwordx2 v[168:169], v[140:141], off
	global_load_dwordx2 v[164:165], v[140:141], off offset:32
	global_load_dwordx2 v[162:163], v[140:141], off offset:256
	global_load_dwordx2 v[160:161], v[140:141], off offset:288
	v_or_b32_e32 v156, 32, v136
	v_ashrrev_i32_e32 v157, 31, v156
	v_lshlrev_b64 v[140:141], 12, v[156:157]
	v_lshl_add_u64 v[140:141], v[138:139], 0, v[140:141]
	global_load_dwordx2 v[158:159], v[140:141], off
	global_load_dwordx2 v[154:155], v[140:141], off offset:32
	global_load_dwordx2 v[152:153], v[140:141], off offset:256
	global_load_dwordx2 v[146:147], v[140:141], off offset:288
	v_or_b32_e32 v148, 48, v136
	v_ashrrev_i32_e32 v149, 31, v148
	v_lshlrev_b64 v[140:141], 12, v[148:149]
	v_lshl_add_u64 v[140:141], v[138:139], 0, v[140:141]
	global_load_dwordx2 v[150:151], v[140:141], off
	global_load_dwordx2 v[144:145], v[140:141], off offset:32
	global_load_dwordx2 v[142:143], v[140:141], off offset:256
	s_nop 0
	global_load_dwordx2 v[140:141], v[140:141], off offset:288
	v_lshlrev_b64 v[182:183], 11, v[136:137]
	s_and_b64 vcc, exec, s[2:3]
	s_mov_b32 s33, s8
	s_mov_b32 s16, s10
	s_mov_b64 s[20:21], s[14:15]
	s_mov_b64 s[18:19], s[12:13]
	v_add_u32_e32 v222, 0x80, v136
	v_ashrrev_i32_e32 v223, 31, v222
	v_lshlrev_b64 v[222:223], 12, v[222:223]
	v_lshl_add_u64 v[222:223], v[138:139], 0, v[222:223]
	global_load_dwordx2 v[186:187], v[222:223], off
	global_load_dwordx2 v[188:189], v[222:223], off offset:32
	global_load_dwordx2 v[190:191], v[222:223], off offset:256
	global_load_dwordx2 v[194:195], v[222:223], off offset:288
	v_add_u32_e32 v222, 0x90, v136
	v_ashrrev_i32_e32 v223, 31, v222
	v_lshlrev_b64 v[222:223], 12, v[222:223]
	v_lshl_add_u64 v[222:223], v[138:139], 0, v[222:223]
	global_load_dwordx2 v[196:197], v[222:223], off
	global_load_dwordx2 v[200:201], v[222:223], off offset:32
	global_load_dwordx2 v[202:203], v[222:223], off offset:256
	global_load_dwordx2 v[204:205], v[222:223], off offset:288
	v_add_u32_e32 v222, 0xa0, v136
	v_ashrrev_i32_e32 v223, 31, v222
	v_lshlrev_b64 v[222:223], 12, v[222:223]
	v_lshl_add_u64 v[222:223], v[138:139], 0, v[222:223]
	global_load_dwordx2 v[206:207], v[222:223], off
	global_load_dwordx2 v[208:209], v[222:223], off offset:32
	global_load_dwordx2 v[210:211], v[222:223], off offset:256
	global_load_dwordx2 v[212:213], v[222:223], off offset:288
	v_add_u32_e32 v222, 0xb0, v136
	v_ashrrev_i32_e32 v223, 31, v222
	v_lshlrev_b64 v[222:223], 12, v[222:223]
	v_lshl_add_u64 v[222:223], v[138:139], 0, v[222:223]
	global_load_dwordx2 v[214:215], v[222:223], off
	global_load_dwordx2 v[216:217], v[222:223], off offset:32
	global_load_dwordx2 v[218:219], v[222:223], off offset:256
	global_load_dwordx2 v[220:221], v[222:223], off offset:288
	s_waitcnt vmcnt(16)
; __device__ __forceinline__ unsigned cvt_pk_bf16(float lo, float hi) { unsigned r; asm volatile("s_nop 0\n\tv_cvt_pk_bf16_f32 %0, %1, %2\n\ts_nop 1" : "=v"(r) : "v"(lo), "v"(hi)); return r; }
; __device__ __forceinline__ float bflo(unsigned w) { return __uint_as_float(w << 16); }
; __device__ __forceinline__ float bfhi(unsigned w) { return __uint_as_float(w & 0xffff0000u); }
;     __device__ __forceinline__ void operator()(f32x4 (&acc)[2][2][4][2], const Unit& u, int wr, int wc, int fr, int fq) const {
;     ...
;             for (int m = 0; m < 4; ++m) { const size_t row = row0 + ai * 128 + m * 16;
; #pragma unroll
;                 for (int bj = 0; bj < 2; ++bj)
; #pragma unroll
;                     for (int n = 0; n < 2; ++n) { const int col = col0 + bj * 128 + n * 16; const u32x2 g2 = gw[m][bj][n];
;                         const f32x4 gv = (f32x4){bflo(g2.x), bfhi(g2.x), bflo(g2.y), bfhi(g2.y)};
;                         const f32x4 o = gv * acc[ai][bj][m][n]; u32x2 w; w.x = cvt_pk_bf16(o[0], o[1]); w.y = cvt_pk_bf16(o[2], o[3]); *(u32x2*)(tmp + row * 1024 + col) = w; } }
	v_lshlrev_b32_e32 v184, 16, v174
	v_and_b32_e32 v185, 0xffff0000, v174
	v_lshlrev_b32_e32 v174, 16, v175
	v_and_b32_e32 v175, 0xffff0000, v175
	v_pk_mul_f32 v[126:127], v[126:127], v[174:175]
	v_pk_mul_f32 v[124:125], v[124:125], v[184:185]
	v_lshlrev_b32_e32 v174, 16, v177
	v_cvt_pk_bf16_f32 v124, v124, v125
	v_cvt_pk_bf16_f32 v125, v126, v127
	v_lshl_add_u64 v[126:127], s[4:5], 0, v[182:183]
	v_lshl_add_u64 v[126:127], v[126:127], 0, v[134:135]
	global_store_dwordx2 v[126:127], v[124:125], off
	v_lshlrev_b32_e32 v124, 16, v176
	v_and_b32_e32 v125, 0xffff0000, v176
	v_and_b32_e32 v175, 0xffff0000, v177
	v_pk_mul_f32 v[120:121], v[120:121], v[124:125]
	v_pk_mul_f32 v[122:123], v[122:123], v[174:175]
	v_cvt_pk_bf16_f32 v120, v120, v121
	s_nop 0
	v_cvt_pk_bf16_f32 v121, v122, v123
	global_store_dwordx2 v[126:127], v[120:121], off offset:32
	v_lshlrev_b32_e32 v120, 16, v178
	v_and_b32_e32 v121, 0xffff0000, v178
	v_lshlrev_b32_e32 v122, 16, v179
	v_and_b32_e32 v123, 0xffff0000, v179
	v_pk_mul_f32 v[116:117], v[116:117], v[120:121]
	v_pk_mul_f32 v[118:119], v[118:119], v[122:123]
	v_cvt_pk_bf16_f32 v116, v116, v117
	s_nop 0
	v_cvt_pk_bf16_f32 v117, v118, v119
	global_store_dwordx2 v[126:127], v[116:117], off offset:256
	v_lshlrev_b32_e32 v116, 16, v180
	v_and_b32_e32 v117, 0xffff0000, v180
	v_lshlrev_b32_e32 v118, 16, v181
	v_and_b32_e32 v119, 0xffff0000, v181
	v_pk_mul_f32 v[114:115], v[114:115], v[118:119]
	v_pk_mul_f32 v[112:113], v[112:113], v[116:117]
	v_lshlrev_b32_e32 v116, 16, v169
	v_cvt_pk_bf16_f32 v112, v112, v113
	v_cvt_pk_bf16_f32 v113, v114, v115
	v_lshlrev_b32_e32 v114, 16, v168
	v_and_b32_e32 v115, 0xffff0000, v168
	v_and_b32_e32 v117, 0xffff0000, v169
	global_store_dwordx2 v[126:127], v[112:113], off offset:288
	v_lshlrev_b64 v[112:113], 11, v[166:167]
	v_pk_mul_f32 v[110:111], v[110:111], v[116:117]
	v_pk_mul_f32 v[108:109], v[108:109], v[114:115]
	s_nop 0
	v_cvt_pk_bf16_f32 v108, v108, v109
	v_cvt_pk_bf16_f32 v109, v110, v111
	v_lshl_add_u64 v[110:111], s[4:5], 0, v[112:113]
	v_lshl_add_u64 v[110:111], v[110:111], 0, v[134:135]
	global_store_dwordx2 v[110:111], v[108:109], off
	v_lshlrev_b32_e32 v108, 16, v164
	v_and_b32_e32 v109, 0xffff0000, v164
	v_lshlrev_b32_e32 v112, 16, v165
	v_and_b32_e32 v113, 0xffff0000, v165
	v_pk_mul_f32 v[104:105], v[104:105], v[108:109]
	v_pk_mul_f32 v[106:107], v[106:107], v[112:113]
	v_cvt_pk_bf16_f32 v104, v104, v105
	s_nop 0
	v_cvt_pk_bf16_f32 v105, v106, v107
	global_store_dwordx2 v[110:111], v[104:105], off offset:32
	v_lshlrev_b32_e32 v104, 16, v162
	v_and_b32_e32 v105, 0xffff0000, v162
	v_lshlrev_b32_e32 v106, 16, v163
	v_and_b32_e32 v107, 0xffff0000, v163
	v_pk_mul_f32 v[100:101], v[100:101], v[104:105]
	v_pk_mul_f32 v[102:103], v[102:103], v[106:107]
	v_cvt_pk_bf16_f32 v100, v100, v101
	s_nop 0
	v_cvt_pk_bf16_f32 v101, v102, v103
	global_store_dwordx2 v[110:111], v[100:101], off offset:256
	v_lshlrev_b32_e32 v100, 16, v160
	v_and_b32_e32 v101, 0xffff0000, v160
	v_lshlrev_b32_e32 v102, 16, v161
	v_and_b32_e32 v103, 0xffff0000, v161
	v_pk_mul_f32 v[92:93], v[92:93], v[100:101]
	v_pk_mul_f32 v[94:95], v[94:95], v[102:103]
	v_cvt_pk_bf16_f32 v92, v92, v93
	v_lshlrev_b32_e32 v100, 16, v159
	v_cvt_pk_bf16_f32 v93, v94, v95
	global_store_dwordx2 v[110:111], v[92:93], off offset:288
	v_lshlrev_b64 v[92:93], 11, v[156:157]
	v_lshlrev_b32_e32 v94, 16, v158
	v_and_b32_e32 v95, 0xffff0000, v158
	v_and_b32_e32 v101, 0xffff0000, v159
	v_pk_mul_f32 v[94:95], v[96:97], v[94:95]
	v_lshl_add_u64 v[92:93], s[4:5], 0, v[92:93]
	v_pk_mul_f32 v[98:99], v[98:99], v[100:101]
	v_cvt_pk_bf16_f32 v94, v94, v95
	v_lshl_add_u64 v[92:93], v[92:93], 0, v[134:135]
	v_cvt_pk_bf16_f32 v95, v98, v99
	global_store_dwordx2 v[92:93], v[94:95], off
	v_lshlrev_b32_e32 v94, 16, v154
	v_and_b32_e32 v95, 0xffff0000, v154
	v_lshlrev_b32_e32 v96, 16, v155
	v_and_b32_e32 v97, 0xffff0000, v155
	v_pk_mul_f32 v[88:89], v[88:89], v[94:95]
	v_pk_mul_f32 v[90:91], v[90:91], v[96:97]
	v_cvt_pk_bf16_f32 v88, v88, v89
	v_add_u32_e32 v94, 0xa0, v136
	v_cvt_pk_bf16_f32 v89, v90, v91
	global_store_dwordx2 v[92:93], v[88:89], off offset:32
	v_lshlrev_b32_e32 v88, 16, v152
	v_and_b32_e32 v89, 0xffff0000, v152
	v_lshlrev_b32_e32 v90, 16, v153
	v_and_b32_e32 v91, 0xffff0000, v153
	v_pk_mul_f32 v[84:85], v[84:85], v[88:89]
	v_pk_mul_f32 v[86:87], v[86:87], v[90:91]
	v_cvt_pk_bf16_f32 v84, v84, v85
	v_ashrrev_i32_e32 v95, 31, v94
	v_cvt_pk_bf16_f32 v85, v86, v87
	global_store_dwordx2 v[92:93], v[84:85], off offset:256
	v_lshlrev_b32_e32 v84, 16, v146
	v_and_b32_e32 v85, 0xffff0000, v146
	v_lshlrev_b32_e32 v86, 16, v147
	v_and_b32_e32 v87, 0xffff0000, v147
	v_pk_mul_f32 v[76:77], v[76:77], v[84:85]
	v_pk_mul_f32 v[78:79], v[78:79], v[86:87]
	v_cvt_pk_bf16_f32 v76, v76, v77
	v_lshlrev_b32_e32 v84, 16, v151
	v_cvt_pk_bf16_f32 v77, v78, v79
	global_store_dwordx2 v[92:93], v[76:77], off offset:288
	v_lshlrev_b64 v[76:77], 11, v[148:149]
	v_lshlrev_b32_e32 v78, 16, v150
	v_and_b32_e32 v79, 0xffff0000, v150
	v_and_b32_e32 v85, 0xffff0000, v151
	v_pk_mul_f32 v[78:79], v[80:81], v[78:79]
	v_lshl_add_u64 v[76:77], s[4:5], 0, v[76:77]
	v_pk_mul_f32 v[82:83], v[82:83], v[84:85]
	v_cvt_pk_bf16_f32 v78, v78, v79
	v_lshl_add_u64 v[76:77], v[76:77], 0, v[134:135]
	v_cvt_pk_bf16_f32 v79, v82, v83
	global_store_dwordx2 v[76:77], v[78:79], off
	v_lshlrev_b32_e32 v78, 16, v144
	v_and_b32_e32 v79, 0xffff0000, v144
	v_lshlrev_b32_e32 v80, 16, v145
	v_and_b32_e32 v81, 0xffff0000, v145
	v_pk_mul_f32 v[72:73], v[72:73], v[78:79]
	v_pk_mul_f32 v[74:75], v[74:75], v[80:81]
	v_cvt_pk_bf16_f32 v72, v72, v73
	v_add_u32_e32 v84, 0x90, v136
	v_cvt_pk_bf16_f32 v73, v74, v75
	global_store_dwordx2 v[76:77], v[72:73], off offset:32
	v_lshlrev_b32_e32 v72, 16, v142
	v_and_b32_e32 v73, 0xffff0000, v142
	v_lshlrev_b32_e32 v74, 16, v143
	v_and_b32_e32 v75, 0xffff0000, v143
	v_pk_mul_f32 v[68:69], v[68:69], v[72:73]
	v_pk_mul_f32 v[70:71], v[70:71], v[74:75]
	v_cvt_pk_bf16_f32 v68, v68, v69
	v_add_u32_e32 v74, 0x80, v136
	v_cvt_pk_bf16_f32 v69, v70, v71
	global_store_dwordx2 v[76:77], v[68:69], off offset:256
	v_lshlrev_b32_e32 v68, 16, v140
	v_and_b32_e32 v69, 0xffff0000, v140
	v_lshlrev_b32_e32 v70, 16, v141
	v_and_b32_e32 v71, 0xffff0000, v141
	v_pk_mul_f32 v[64:65], v[64:65], v[68:69]
	v_pk_mul_f32 v[66:67], v[66:67], v[70:71]
	v_cvt_pk_bf16_f32 v64, v64, v65
	v_ashrrev_i32_e32 v75, 31, v74
	v_cvt_pk_bf16_f32 v65, v66, v67
	global_store_dwordx2 v[76:77], v[64:65], off offset:288
	v_ashrrev_i32_e32 v85, 31, v84
	v_add_u32_e32 v70, 0xb0, v136
	v_ashrrev_i32_e32 v71, 31, v70
	s_nop 0
	v_lshlrev_b64 v[74:75], 11, v[74:75]
	s_waitcnt vmcnt(16)
; __device__ __forceinline__ unsigned cvt_pk_bf16(float lo, float hi) { unsigned r; asm volatile("s_nop 0\n\tv_cvt_pk_bf16_f32 %0, %1, %2\n\ts_nop 1" : "=v"(r) : "v"(lo), "v"(hi)); return r; }
; #define PG8_WAIT_V(n) asm volatile("s_waitcnt vmcnt(" #n ")" ::: "memory")
; #define PG8_BAR __builtin_amdgcn_s_barrier()
; __device__ __forceinline__ float bflo(unsigned w) { return __uint_as_float(w << 16); }
; __device__ __forceinline__ float bfhi(unsigned w) { return __uint_as_float(w & 0xffff0000u); }
; template <class Epi, class Sched>
; __device__ __forceinline__ void gemm_phase(PG8_LAS unsigned char* lds, const Gemm g, const Sched& S, const Epi& E, int tid_in) {
;     ...
;         if (!has_next) break;
; #pragma unroll
;         for (int a = 0; a < 2; ++a)
; #pragma unroll
;             for (int b = 0; b < 2; ++b)
; #pragma unroll
;                 for (int m = 0; m < 4; ++m)
; #pragma unroll
;                     for (int n = 0; n < 2; ++n) acc[a][b][m][n] = (f32x4){0.f, 0.f, 0.f, 0.f};
;         cur = nxt; cA = nA; cB = nB; ++ui;
;     }
;     PG8_WAIT_V(0);
;     if (wr == 0) PG8_BAR;
;     PG8_BAR;
;     __device__ __forceinline__ void operator()(f32x4 (&acc)[2][2][4][2], const Unit& u, int wr, int wc, int fr, int fq) const {
;     ...
;             for (int m = 0; m < 4; ++m) { const size_t row = row0 + ai * 128 + m * 16;
; #pragma unroll
;                 for (int bj = 0; bj < 2; ++bj)
; #pragma unroll
;                     for (int n = 0; n < 2; ++n) { const int col = col0 + bj * 128 + n * 16; const u32x2 g2 = gw[m][bj][n];
;                         const f32x4 gv = (f32x4){bflo(g2.x), bfhi(g2.x), bflo(g2.y), bfhi(g2.y)};
;                         const f32x4 o = gv * acc[ai][bj][m][n]; u32x2 w; w.x = cvt_pk_bf16(o[0], o[1]); w.y = cvt_pk_bf16(o[2], o[3]); *(u32x2*)(tmp + row * 1024 + col) = w; } }
	v_lshlrev_b32_e32 v104, 16, v186
	v_and_b32_e32 v105, 0xffff0000, v186
	v_lshlrev_b32_e32 v76, 16, v187
	v_and_b32_e32 v77, 0xffff0000, v187
	v_pk_mul_f32 v[62:63], v[62:63], v[76:77]
	v_pk_mul_f32 v[60:61], v[60:61], v[104:105]
	s_nop 0
	v_cvt_pk_bf16_f32 v60, v60, v61
	v_cvt_pk_bf16_f32 v61, v62, v63
	v_lshl_add_u64 v[62:63], s[4:5], 0, v[74:75]
	v_lshl_add_u64 v[62:63], v[62:63], 0, v[134:135]
	global_store_dwordx2 v[62:63], v[60:61], off
	v_lshlrev_b32_e32 v60, 16, v188
	v_and_b32_e32 v61, 0xffff0000, v188
	v_lshlrev_b32_e32 v74, 16, v189
	v_and_b32_e32 v75, 0xffff0000, v189
	v_pk_mul_f32 v[56:57], v[56:57], v[60:61]
	v_pk_mul_f32 v[58:59], v[58:59], v[74:75]
	v_cvt_pk_bf16_f32 v56, v56, v57
	s_nop 0
	v_cvt_pk_bf16_f32 v57, v58, v59
	global_store_dwordx2 v[62:63], v[56:57], off offset:32
	v_lshlrev_b32_e32 v56, 16, v190
	v_and_b32_e32 v57, 0xffff0000, v190
	v_lshlrev_b32_e32 v58, 16, v191
	v_and_b32_e32 v59, 0xffff0000, v191
	v_pk_mul_f32 v[52:53], v[52:53], v[56:57]
	v_pk_mul_f32 v[54:55], v[54:55], v[58:59]
	v_cvt_pk_bf16_f32 v52, v52, v53
	s_nop 0
	v_cvt_pk_bf16_f32 v53, v54, v55
	global_store_dwordx2 v[62:63], v[52:53], off offset:256
	v_lshlrev_b32_e32 v52, 16, v194
	v_and_b32_e32 v53, 0xffff0000, v194
	v_lshlrev_b32_e32 v54, 16, v195
	v_and_b32_e32 v55, 0xffff0000, v195
	v_pk_mul_f32 v[44:45], v[44:45], v[52:53]
	v_pk_mul_f32 v[46:47], v[46:47], v[54:55]
	v_cvt_pk_bf16_f32 v44, v44, v45
	v_lshlrev_b32_e32 v52, 16, v197
	v_cvt_pk_bf16_f32 v45, v46, v47
	global_store_dwordx2 v[62:63], v[44:45], off offset:288
	v_lshlrev_b64 v[44:45], 11, v[84:85]
	v_lshlrev_b32_e32 v46, 16, v196
	v_and_b32_e32 v47, 0xffff0000, v196
	v_and_b32_e32 v53, 0xffff0000, v197
	v_pk_mul_f32 v[46:47], v[48:49], v[46:47]
	v_lshl_add_u64 v[44:45], s[4:5], 0, v[44:45]
	v_pk_mul_f32 v[50:51], v[50:51], v[52:53]
	v_cvt_pk_bf16_f32 v46, v46, v47
	v_lshl_add_u64 v[44:45], v[44:45], 0, v[134:135]
	v_cvt_pk_bf16_f32 v47, v50, v51
	global_store_dwordx2 v[44:45], v[46:47], off
	v_lshlrev_b32_e32 v46, 16, v200
	v_and_b32_e32 v47, 0xffff0000, v200
	v_lshlrev_b32_e32 v48, 16, v201
	v_and_b32_e32 v49, 0xffff0000, v201
	v_pk_mul_f32 v[40:41], v[40:41], v[46:47]
	v_pk_mul_f32 v[42:43], v[42:43], v[48:49]
	v_cvt_pk_bf16_f32 v40, v40, v41
	s_nop 0
	v_cvt_pk_bf16_f32 v41, v42, v43
	global_store_dwordx2 v[44:45], v[40:41], off offset:32
	v_lshlrev_b32_e32 v40, 16, v202
	v_and_b32_e32 v41, 0xffff0000, v202
	v_lshlrev_b32_e32 v42, 16, v203
	v_and_b32_e32 v43, 0xffff0000, v203
	v_pk_mul_f32 v[36:37], v[36:37], v[40:41]
	v_pk_mul_f32 v[38:39], v[38:39], v[42:43]
	v_cvt_pk_bf16_f32 v36, v36, v37
	s_nop 0
	v_cvt_pk_bf16_f32 v37, v38, v39
	global_store_dwordx2 v[44:45], v[36:37], off offset:256
	v_lshlrev_b32_e32 v36, 16, v204
	v_and_b32_e32 v37, 0xffff0000, v204
	v_lshlrev_b32_e32 v38, 16, v205
	v_and_b32_e32 v39, 0xffff0000, v205
	v_pk_mul_f32 v[28:29], v[28:29], v[36:37]
	v_pk_mul_f32 v[30:31], v[30:31], v[38:39]
	v_cvt_pk_bf16_f32 v28, v28, v29
	v_lshlrev_b32_e32 v36, 16, v207
	v_cvt_pk_bf16_f32 v29, v30, v31
	global_store_dwordx2 v[44:45], v[28:29], off offset:288
	v_lshlrev_b64 v[28:29], 11, v[94:95]
	v_lshlrev_b32_e32 v30, 16, v206
	v_and_b32_e32 v31, 0xffff0000, v206
	v_and_b32_e32 v37, 0xffff0000, v207
	v_pk_mul_f32 v[30:31], v[32:33], v[30:31]
	v_lshl_add_u64 v[28:29], s[4:5], 0, v[28:29]
	v_pk_mul_f32 v[34:35], v[34:35], v[36:37]
	v_cvt_pk_bf16_f32 v30, v30, v31
	v_lshl_add_u64 v[28:29], v[28:29], 0, v[134:135]
	v_cvt_pk_bf16_f32 v31, v34, v35
	global_store_dwordx2 v[28:29], v[30:31], off
	v_lshlrev_b32_e32 v30, 16, v208
	v_and_b32_e32 v31, 0xffff0000, v208
	v_lshlrev_b32_e32 v32, 16, v209
	v_and_b32_e32 v33, 0xffff0000, v209
	v_pk_mul_f32 v[24:25], v[24:25], v[30:31]
	v_pk_mul_f32 v[26:27], v[26:27], v[32:33]
	v_cvt_pk_bf16_f32 v24, v24, v25
	s_nop 0
	v_cvt_pk_bf16_f32 v25, v26, v27
	global_store_dwordx2 v[28:29], v[24:25], off offset:32
	v_lshlrev_b32_e32 v24, 16, v210
	v_and_b32_e32 v25, 0xffff0000, v210
	v_lshlrev_b32_e32 v26, 16, v211
	v_and_b32_e32 v27, 0xffff0000, v211
	v_pk_mul_f32 v[20:21], v[20:21], v[24:25]
	v_pk_mul_f32 v[22:23], v[22:23], v[26:27]
	v_cvt_pk_bf16_f32 v20, v20, v21
	s_nop 0
	v_cvt_pk_bf16_f32 v21, v22, v23
	global_store_dwordx2 v[28:29], v[20:21], off offset:256
	v_lshlrev_b32_e32 v20, 16, v212
	v_and_b32_e32 v21, 0xffff0000, v212
	v_lshlrev_b32_e32 v22, 16, v213
	v_and_b32_e32 v23, 0xffff0000, v213
	v_pk_mul_f32 v[12:13], v[12:13], v[20:21]
	v_pk_mul_f32 v[14:15], v[14:15], v[22:23]
	v_cvt_pk_bf16_f32 v12, v12, v13
	v_lshlrev_b32_e32 v20, 16, v215
	v_cvt_pk_bf16_f32 v13, v14, v15
	global_store_dwordx2 v[28:29], v[12:13], off offset:288
	v_lshlrev_b64 v[12:13], 11, v[70:71]
	v_lshlrev_b32_e32 v14, 16, v214
	v_and_b32_e32 v15, 0xffff0000, v214
	v_and_b32_e32 v21, 0xffff0000, v215
	v_pk_mul_f32 v[14:15], v[16:17], v[14:15]
	v_lshl_add_u64 v[12:13], s[4:5], 0, v[12:13]
	v_pk_mul_f32 v[18:19], v[18:19], v[20:21]
	v_cvt_pk_bf16_f32 v14, v14, v15
	v_lshl_add_u64 v[12:13], v[12:13], 0, v[134:135]
	v_cvt_pk_bf16_f32 v15, v18, v19
	global_store_dwordx2 v[12:13], v[14:15], off
	v_lshlrev_b32_e32 v14, 16, v216
	v_and_b32_e32 v15, 0xffff0000, v216
	v_lshlrev_b32_e32 v16, 16, v217
	v_and_b32_e32 v17, 0xffff0000, v217
	v_pk_mul_f32 v[8:9], v[8:9], v[14:15]
	v_pk_mul_f32 v[10:11], v[10:11], v[16:17]
	v_cvt_pk_bf16_f32 v8, v8, v9
	s_nop 0
	v_cvt_pk_bf16_f32 v9, v10, v11
	global_store_dwordx2 v[12:13], v[8:9], off offset:32
	v_lshlrev_b32_e32 v8, 16, v218
	v_and_b32_e32 v9, 0xffff0000, v218
	v_lshlrev_b32_e32 v10, 16, v219
	v_and_b32_e32 v11, 0xffff0000, v219
	v_pk_mul_f32 v[4:5], v[4:5], v[8:9]
	v_pk_mul_f32 v[6:7], v[6:7], v[10:11]
	v_cvt_pk_bf16_f32 v4, v4, v5
	s_nop 0
	v_cvt_pk_bf16_f32 v5, v6, v7
	global_store_dwordx2 v[12:13], v[4:5], off offset:256
	v_lshlrev_b32_e32 v4, 16, v220
	v_and_b32_e32 v5, 0xffff0000, v220
	v_lshlrev_b32_e32 v6, 16, v221
	v_and_b32_e32 v7, 0xffff0000, v221
	v_pk_mul_f32 v[0:1], v[0:1], v[4:5]
	v_pk_mul_f32 v[2:3], v[2:3], v[6:7]
	v_cvt_pk_bf16_f32 v0, v0, v1
	s_nop 0
	v_cvt_pk_bf16_f32 v1, v2, v3
	s_nop 1
	global_store_dwordx2 v[12:13], v[0:1], off offset:288
	s_cbranch_vccz .LBB0_343
	s_waitcnt vmcnt(0)
	s_cmpk_gt_u32 s24, 0xff
	s_cbranch_scc1 .LBB0_354
	s_barrier

; #define PG8_STAGE(bufoff, gbase, voff) do { _Pragma("unroll") for (int _i = 0; _i < 2; ++_i) \
;         __builtin_amdgcn_global_load_lds((const unsigned*)((const char*)(gbase) + (voff)[_i]), (PG8_LAS unsigned*)(lds + (bufoff) + ldsw + _i * 8192), 16, 0, 0); } while (0)
; #define PG8_LDA(dst, b, h) do { _Pragma("unroll") for (int m = 0; m < 4; ++m) _Pragma("unroll") for (int k = 0; k < 2; ++k) dst[m][k] = *(const PG8_LAS bf16x8*)(lds + PG8_SA(b, h) + aoff + m * 2048 + k * 1024); } while (0)
; #define PG8_LDB(dst, b, h) do { _Pragma("unroll") for (int n = 0; n < 2; ++n) _Pragma("unroll") for (int k = 0; k < 2; ++k) dst[n][k] = *(const PG8_LAS bf16x8*)(lds + PG8_SB(b, h) + boff + n * 2048 + k * 1024); } while (0)
; #define PG8_MMA(ai, bj, At, Bt) do { __builtin_amdgcn_s_setprio(1); _Pragma("unroll") for (int m = 0; m < 4; ++m) _Pragma("unroll") for (int n = 0; n < 2; ++n) _Pragma("unroll") for (int k = 0; k < 2; ++k) \
;         acc[ai][bj][m][n] = __builtin_amdgcn_mfma_f32_16x16x32_bf16(Bt[n][k], At[m][k], acc[ai][bj][m][n], 0, 0, 0); __builtin_amdgcn_s_setprio(0); } while (0)
; #define PG8_WAIT_L(n) asm volatile("s_waitcnt lgkmcnt(" #n ")" ::: "memory")
; #define PG8_BAR __builtin_amdgcn_s_barrier()
; #define PG8_SCHED __builtin_amdgcn_sched_barrier(0)
; template <class Epi, class Sched>
; __device__ __forceinline__ void gemm_phase(PG8_LAS unsigned char* lds, const Gemm g, const Sched& S, const Epi& E, int tid_in) {
;     ...
;             PG8_LDB(B0, 0, 0); PG8_SCHED; PG8_LDA(At, 0, 0); PG8_STAGE(PG8_SA(1, 1), a1 + hstep, voffA);
;             PG8_WAIT_L(8); PG8_BAR; PG8_WAIT_L(0); PG8_MMA(0, 0, At, B0); PG8_BAR; PG8_SCHED;
;             PG8_LDB(B1, 0, 1); PG8_STAGE(PG8_SB(0, 0), b2, voffB);
;             PG8_BAR; PG8_WAIT_L(0); PG8_MMA(0, 1, At, B1); PG8_BAR;
;             PG8_LDA(At, 0, 1); PG8_STAGE(PG8_SA(0, 0), a2, voffA);
;             PG8_BAR; PG8_WAIT_L(0); PG8_MMA(1, 0, At, B0); PG8_BAR; PG8_SCHED;
.LBB0_388:
	s_add_u32 s28, s26, 0xfffc0080
	s_addc_u32 s29, s27, -1
	s_add_i32 s38, 0, 0x10000
	v_add_u32_e32 v140, s38, v246
	ds_read_b128 v[128:131], v140
	ds_read_b128 v[132:135], v140 offset:1024
	ds_read_b128 v[136:139], v140 offset:2048
	ds_read_b128 v[140:143], v140 offset:3072
	s_cmp_eq_u32 s37, 12
	s_cselect_b32 s31, s1, s29
	s_cselect_b32 s30, s19, s28
	s_cselect_b32 s29, s17, s36
	s_cselect_b32 s28, s25, s33
	v_lshl_add_u64 v[176:177], s[26:27], 0, v[210:211]
	s_add_i32 m0, s73, 0xc000
	ds_read_b128 v[144:147], v251
	ds_read_b128 v[148:151], v251 offset:1024
	ds_read_b128 v[152:155], v251 offset:2048
	ds_read_b128 v[156:159], v251 offset:3072
	ds_read_b128 v[160:163], v251 offset:4096
	ds_read_b128 v[164:167], v251 offset:5120
	ds_read_b128 v[168:171], v251 offset:6144
	ds_read_b128 v[172:175], v251 offset:7168
	global_load_lds_dwordx4 v[176:177], off
	v_lshl_add_u64 v[176:177], s[26:27], 0, v[212:213]
	s_add_i32 m0, s73, 0xe000
	s_nop 0
	global_load_lds_dwordx4 v[176:177], off
	s_waitcnt lgkmcnt(8)
	s_barrier
	s_waitcnt lgkmcnt(0)
	s_setprio 1
	s_waitcnt lgkmcnt(0)
	v_mfma_f32_16x16x32_bf16 v[124:127], v[128:131], v[144:147], v[124:127]
	v_mfma_f32_16x16x32_bf16 v[120:123], v[136:139], v[144:147], v[120:123]
	v_mfma_f32_16x16x32_bf16 v[108:111], v[128:131], v[152:155], v[108:111]
	v_mfma_f32_16x16x32_bf16 v[104:107], v[136:139], v[152:155], v[104:107]
	v_mfma_f32_16x16x32_bf16 v[92:95], v[128:131], v[160:163], v[92:95]
	v_mfma_f32_16x16x32_bf16 v[88:91], v[136:139], v[160:163], v[88:91]
	v_mfma_f32_16x16x32_bf16 v[76:79], v[128:131], v[168:171], v[76:79]
	v_mfma_f32_16x16x32_bf16 v[72:75], v[136:139], v[168:171], v[72:75]
	v_mfma_f32_16x16x32_bf16 v[124:127], v[132:135], v[148:151], v[124:127]
	v_mfma_f32_16x16x32_bf16 v[120:123], v[140:143], v[148:151], v[120:123]
	v_mfma_f32_16x16x32_bf16 v[108:111], v[132:135], v[156:159], v[108:111]
	v_mfma_f32_16x16x32_bf16 v[104:107], v[140:143], v[156:159], v[104:107]
	v_mfma_f32_16x16x32_bf16 v[92:95], v[132:135], v[164:167], v[92:95]
	v_mfma_f32_16x16x32_bf16 v[88:91], v[140:143], v[164:167], v[88:91]
	v_mfma_f32_16x16x32_bf16 v[76:79], v[132:135], v[172:175], v[76:79]
	v_mfma_f32_16x16x32_bf16 v[72:75], v[140:143], v[172:175], v[72:75]
	s_setprio 0
	s_barrier
	s_add_i32 s40, 0, 0x14000
	s_add_i32 s38, s38, s72
	v_add_u32_e32 v188, s40, v246
	v_lshl_add_u64 v[194:195], s[28:29], 0, v[202:203]
	s_mov_b32 m0, s38
	ds_read_b128 v[176:179], v188
	ds_read_b128 v[180:183], v188 offset:1024
	ds_read_b128 v[184:187], v188 offset:2048
	ds_read_b128 v[188:191], v188 offset:3072
	global_load_lds_dwordx4 v[194:195], off
	v_lshl_add_u64 v[196:197], s[28:29], 0, v[206:207]
	s_add_i32 m0, s38, 0x2000
	s_nop 0
	global_load_lds_dwordx4 v[196:197], off
	s_barrier
	s_waitcnt lgkmcnt(0)
	s_setprio 1
	s_waitcnt lgkmcnt(0)
	v_mfma_f32_16x16x32_bf16 v[116:119], v[176:179], v[144:147], v[116:119]
	v_mfma_f32_16x16x32_bf16 v[112:115], v[184:187], v[144:147], v[112:115]
	v_mfma_f32_16x16x32_bf16 v[100:103], v[176:179], v[152:155], v[100:103]
	v_mfma_f32_16x16x32_bf16 v[96:99], v[184:187], v[152:155], v[96:99]
	v_mfma_f32_16x16x32_bf16 v[84:87], v[176:179], v[160:163], v[84:87]
	v_mfma_f32_16x16x32_bf16 v[80:83], v[184:187], v[160:163], v[80:83]
	v_mfma_f32_16x16x32_bf16 v[68:71], v[176:179], v[168:171], v[68:71]
	v_mfma_f32_16x16x32_bf16 v[64:67], v[184:187], v[168:171], v[64:67]
	v_mfma_f32_16x16x32_bf16 v[116:119], v[180:183], v[148:151], v[116:119]
	v_mfma_f32_16x16x32_bf16 v[112:115], v[188:191], v[148:151], v[112:115]
	v_mfma_f32_16x16x32_bf16 v[100:103], v[180:183], v[156:159], v[100:103]
	v_mfma_f32_16x16x32_bf16 v[96:99], v[188:191], v[156:159], v[96:99]
	v_mfma_f32_16x16x32_bf16 v[84:87], v[180:183], v[164:167], v[84:87]
	v_mfma_f32_16x16x32_bf16 v[80:83], v[188:191], v[164:167], v[80:83]
	v_mfma_f32_16x16x32_bf16 v[68:71], v[180:183], v[172:175], v[68:71]
	v_mfma_f32_16x16x32_bf16 v[64:67], v[188:191], v[172:175], v[64:67]
	s_setprio 0
	s_mov_b32 m0, s73
	v_lshl_add_u64 v[214:215], s[30:31], 0, v[200:201]
	s_barrier
	ds_read_b128 v[144:147], v251 offset:16384
	ds_read_b128 v[148:151], v251 offset:17408
	ds_read_b128 v[152:155], v251 offset:18432
	ds_read_b128 v[156:159], v251 offset:19456
	ds_read_b128 v[160:163], v251 offset:20480
	ds_read_b128 v[164:167], v251 offset:21504
	ds_read_b128 v[168:171], v251 offset:22528
	ds_read_b128 v[172:175], v251 offset:23552
	global_load_lds_dwordx4 v[214:215], off
	v_lshl_add_u64 v[216:217], s[30:31], 0, v[204:205]
	s_mov_b32 m0, s76
	s_nop 0
	global_load_lds_dwordx4 v[216:217], off
	s_barrier
	s_waitcnt lgkmcnt(0)
	s_setprio 1
	s_waitcnt lgkmcnt(0)
	v_mfma_f32_16x16x32_bf16 v[60:63], v[128:131], v[144:147], v[60:63]
	v_mfma_f32_16x16x32_bf16 v[56:59], v[136:139], v[144:147], v[56:59]
	v_mfma_f32_16x16x32_bf16 v[44:47], v[128:131], v[152:155], v[44:47]
	v_mfma_f32_16x16x32_bf16 v[40:43], v[136:139], v[152:155], v[40:43]
	v_mfma_f32_16x16x32_bf16 v[28:31], v[128:131], v[160:163], v[28:31]
	v_mfma_f32_16x16x32_bf16 v[24:27], v[136:139], v[160:163], v[24:27]
	v_mfma_f32_16x16x32_bf16 v[12:15], v[128:131], v[168:171], v[12:15]
	v_mfma_f32_16x16x32_bf16 v[8:11], v[136:139], v[168:171], v[8:11]
	v_mfma_f32_16x16x32_bf16 v[60:63], v[132:135], v[148:151], v[60:63]
	v_mfma_f32_16x16x32_bf16 v[56:59], v[140:143], v[148:151], v[56:59]
	v_mfma_f32_16x16x32_bf16 v[44:47], v[132:135], v[156:159], v[44:47]
	v_mfma_f32_16x16x32_bf16 v[40:43], v[140:143], v[156:159], v[40:43]
	v_mfma_f32_16x16x32_bf16 v[28:31], v[132:135], v[164:167], v[28:31]
	v_mfma_f32_16x16x32_bf16 v[24:27], v[140:143], v[164:167], v[24:27]
	v_mfma_f32_16x16x32_bf16 v[12:15], v[132:135], v[172:175], v[12:15]
	v_mfma_f32_16x16x32_bf16 v[8:11], v[140:143], v[172:175], v[8:11]
	s_setprio 0
	s_barrier
; #define PG8_STAGE(bufoff, gbase, voff) do { _Pragma("unroll") for (int _i = 0; _i < 2; ++_i) \
;         __builtin_amdgcn_global_load_lds((const unsigned*)((const char*)(gbase) + (voff)[_i]), (PG8_LAS unsigned*)(lds + (bufoff) + ldsw + _i * 8192), 16, 0, 0); } while (0)
; #define PG8_LDA(dst, b, h) do { _Pragma("unroll") for (int m = 0; m < 4; ++m) _Pragma("unroll") for (int k = 0; k < 2; ++k) dst[m][k] = *(const PG8_LAS bf16x8*)(lds + PG8_SA(b, h) + aoff + m * 2048 + k * 1024); } while (0)
; #define PG8_LDB(dst, b, h) do { _Pragma("unroll") for (int n = 0; n < 2; ++n) _Pragma("unroll") for (int k = 0; k < 2; ++k) dst[n][k] = *(const PG8_LAS bf16x8*)(lds + PG8_SB(b, h) + boff + n * 2048 + k * 1024); } while (0)
; #define PG8_MMA(ai, bj, At, Bt) do { __builtin_amdgcn_s_setprio(1); _Pragma("unroll") for (int m = 0; m < 4; ++m) _Pragma("unroll") for (int n = 0; n < 2; ++n) _Pragma("unroll") for (int k = 0; k < 2; ++k) \
;         acc[ai][bj][m][n] = __builtin_amdgcn_mfma_f32_16x16x32_bf16(Bt[n][k], At[m][k], acc[ai][bj][m][n], 0, 0, 0); __builtin_amdgcn_s_setprio(0); } while (0)
; #define PG8_WAIT_V(n) asm volatile("s_waitcnt vmcnt(" #n ")" ::: "memory")
; #define PG8_WAIT_L(n) asm volatile("s_waitcnt lgkmcnt(" #n ")" ::: "memory")
; #define PG8_BAR __builtin_amdgcn_s_barrier()
; #define PG8_SCHED __builtin_amdgcn_sched_barrier(0)
; template <class Epi, class Sched>
; __device__ __forceinline__ void gemm_phase(PG8_LAS unsigned char* lds, const Gemm g, const Sched& S, const Epi& E, int tid_in) {
;     ...
;             PG8_STAGE(PG8_SB(0, 1), b2 + hstep, voffB);
;             PG8_WAIT_V(6); PG8_BAR; PG8_MMA(1, 1, At, B1); PG8_BAR;
;             PG8_LDB(B0, 1, 0); PG8_SCHED; PG8_LDA(At, 1, 0); PG8_STAGE(PG8_SA(0, 1), a2 + hstep, voffA);
;             PG8_WAIT_L(8); PG8_BAR; PG8_WAIT_L(0); PG8_MMA(0, 0, At, B0); PG8_BAR; PG8_SCHED;
;             PG8_LDB(B1, 1, 1); PG8_STAGE(PG8_SB(1, 0), b3, voffB);
;             PG8_BAR; PG8_WAIT_L(0); PG8_MMA(0, 1, At, B1); PG8_BAR;
;             PG8_LDA(At, 1, 1); PG8_STAGE(PG8_SA(1, 0), a3, voffA);
	s_add_u32 s38, s28, 0x40000
	s_addc_u32 s39, s29, 0
	s_add_i32 s40, s40, s72
	v_lshl_add_u64 v[128:129], s[38:39], 0, v[202:203]
	s_mov_b32 m0, s40
	s_nop 0
	global_load_lds_dwordx4 v[128:129], off
	v_lshl_add_u64 v[128:129], s[38:39], 0, v[206:207]
	s_add_i32 m0, s40, 0x2000
	s_nop 0
	global_load_lds_dwordx4 v[128:129], off
	s_waitcnt vmcnt(6)
	s_barrier
	s_setprio 1
	v_mfma_f32_16x16x32_bf16 v[52:55], v[176:179], v[144:147], v[52:55]
	v_mfma_f32_16x16x32_bf16 v[48:51], v[184:187], v[144:147], v[48:51]
	v_mfma_f32_16x16x32_bf16 v[36:39], v[176:179], v[152:155], v[36:39]
	v_mfma_f32_16x16x32_bf16 v[32:35], v[184:187], v[152:155], v[32:35]
	v_mfma_f32_16x16x32_bf16 v[20:23], v[176:179], v[160:163], v[20:23]
	v_mfma_f32_16x16x32_bf16 v[16:19], v[184:187], v[160:163], v[16:19]
	v_mfma_f32_16x16x32_bf16 v[4:7], v[176:179], v[168:171], v[4:7]
	v_mfma_f32_16x16x32_bf16 v[0:3], v[184:187], v[168:171], v[0:3]
	v_mfma_f32_16x16x32_bf16 v[52:55], v[180:183], v[148:151], v[52:55]
	v_mfma_f32_16x16x32_bf16 v[48:51], v[188:191], v[148:151], v[48:51]
	v_mfma_f32_16x16x32_bf16 v[36:39], v[180:183], v[156:159], v[36:39]
	v_mfma_f32_16x16x32_bf16 v[32:35], v[188:191], v[156:159], v[32:35]
	v_mfma_f32_16x16x32_bf16 v[20:23], v[180:183], v[164:167], v[20:23]
	v_mfma_f32_16x16x32_bf16 v[16:19], v[188:191], v[164:167], v[16:19]
	v_mfma_f32_16x16x32_bf16 v[4:7], v[180:183], v[172:175], v[4:7]
	v_mfma_f32_16x16x32_bf16 v[0:3], v[188:191], v[172:175], v[0:3]
	s_setprio 0
	s_add_i32 s38, 0, 0x18000
	v_add_u32_e32 v140, s38, v246
	s_barrier
	ds_read_b128 v[128:131], v140
	ds_read_b128 v[132:135], v140 offset:1024
	ds_read_b128 v[136:139], v140 offset:2048
	ds_read_b128 v[140:143], v140 offset:3072
	s_add_u32 s30, s30, 0x40000
	s_addc_u32 s31, s31, 0
	s_mov_b32 m0, s77
	v_lshl_add_u64 v[176:177], s[30:31], 0, v[200:201]
	ds_read_b128 v[144:147], v251 offset:32768
	ds_read_b128 v[148:151], v251 offset:33792
	ds_read_b128 v[152:155], v251 offset:34816
	ds_read_b128 v[156:159], v251 offset:35840
	ds_read_b128 v[160:163], v251 offset:36864
	ds_read_b128 v[164:167], v251 offset:37888
	ds_read_b128 v[168:171], v251 offset:38912
	ds_read_b128 v[172:175], v251 offset:39936
	global_load_lds_dwordx4 v[176:177], off
	v_lshl_add_u64 v[176:177], s[30:31], 0, v[204:205]
	s_mov_b32 m0, s78
	s_nop 0
	global_load_lds_dwordx4 v[176:177], off
	s_waitcnt lgkmcnt(8)
	s_barrier
	s_waitcnt lgkmcnt(0)
	s_setprio 1
	s_waitcnt lgkmcnt(0)
	v_mfma_f32_16x16x32_bf16 v[124:127], v[128:131], v[144:147], v[124:127]
	v_mfma_f32_16x16x32_bf16 v[120:123], v[136:139], v[144:147], v[120:123]
	v_mfma_f32_16x16x32_bf16 v[108:111], v[128:131], v[152:155], v[108:111]
	v_mfma_f32_16x16x32_bf16 v[104:107], v[136:139], v[152:155], v[104:107]
	v_mfma_f32_16x16x32_bf16 v[92:95], v[128:131], v[160:163], v[92:95]
	v_mfma_f32_16x16x32_bf16 v[88:91], v[136:139], v[160:163], v[88:91]
	v_mfma_f32_16x16x32_bf16 v[76:79], v[128:131], v[168:171], v[76:79]
	v_mfma_f32_16x16x32_bf16 v[72:75], v[136:139], v[168:171], v[72:75]
	v_mfma_f32_16x16x32_bf16 v[124:127], v[132:135], v[148:151], v[124:127]
	v_mfma_f32_16x16x32_bf16 v[120:123], v[140:143], v[148:151], v[120:123]
	v_mfma_f32_16x16x32_bf16 v[108:111], v[132:135], v[156:159], v[108:111]
	v_mfma_f32_16x16x32_bf16 v[104:107], v[140:143], v[156:159], v[104:107]
	v_mfma_f32_16x16x32_bf16 v[92:95], v[132:135], v[164:167], v[92:95]
	v_mfma_f32_16x16x32_bf16 v[88:91], v[140:143], v[164:167], v[88:91]
	v_mfma_f32_16x16x32_bf16 v[76:79], v[132:135], v[172:175], v[76:79]
	v_mfma_f32_16x16x32_bf16 v[72:75], v[140:143], v[172:175], v[72:75]
	s_setprio 0
	s_barrier
	s_add_i32 s30, 0, 0x1c000
	s_add_i32 s31, s38, s72
	v_add_u32_e32 v188, s30, v246
	v_lshl_add_u64 v[194:195], v[194:195], 0, s[74:75]
	s_mov_b32 m0, s31
	ds_read_b128 v[176:179], v188
	ds_read_b128 v[180:183], v188 offset:1024
	ds_read_b128 v[184:187], v188 offset:2048
	ds_read_b128 v[188:191], v188 offset:3072
	global_load_lds_dwordx4 v[194:195], off
	v_lshl_add_u64 v[194:195], v[196:197], 0, s[74:75]
	s_add_i32 m0, s31, 0x2000
	s_nop 0
	global_load_lds_dwordx4 v[194:195], off
	s_barrier
	s_waitcnt lgkmcnt(0)
	s_setprio 1
	s_waitcnt lgkmcnt(0)
	v_mfma_f32_16x16x32_bf16 v[116:119], v[176:179], v[144:147], v[116:119]
	v_mfma_f32_16x16x32_bf16 v[112:115], v[184:187], v[144:147], v[112:115]
	v_mfma_f32_16x16x32_bf16 v[100:103], v[176:179], v[152:155], v[100:103]
	v_mfma_f32_16x16x32_bf16 v[96:99], v[184:187], v[152:155], v[96:99]
	v_mfma_f32_16x16x32_bf16 v[84:87], v[176:179], v[160:163], v[84:87]
	v_mfma_f32_16x16x32_bf16 v[80:83], v[184:187], v[160:163], v[80:83]
	v_mfma_f32_16x16x32_bf16 v[68:71], v[176:179], v[168:171], v[68:71]
	v_mfma_f32_16x16x32_bf16 v[64:67], v[184:187], v[168:171], v[64:67]
	v_mfma_f32_16x16x32_bf16 v[116:119], v[180:183], v[148:151], v[116:119]
	v_mfma_f32_16x16x32_bf16 v[112:115], v[188:191], v[148:151], v[112:115]
	v_mfma_f32_16x16x32_bf16 v[100:103], v[180:183], v[156:159], v[100:103]
	v_mfma_f32_16x16x32_bf16 v[96:99], v[188:191], v[156:159], v[96:99]
	v_mfma_f32_16x16x32_bf16 v[84:87], v[180:183], v[164:167], v[84:87]
	v_mfma_f32_16x16x32_bf16 v[80:83], v[188:191], v[164:167], v[80:83]
	v_mfma_f32_16x16x32_bf16 v[68:71], v[180:183], v[172:175], v[68:71]
	v_mfma_f32_16x16x32_bf16 v[64:67], v[188:191], v[172:175], v[64:67]
	s_setprio 0
	s_mov_b32 m0, s80
	v_lshl_add_u64 v[194:195], v[214:215], 0, s[74:75]
	s_barrier
	ds_read_b128 v[144:147], v251 offset:49152
	ds_read_b128 v[148:151], v251 offset:50176
	ds_read_b128 v[152:155], v251 offset:51200
	ds_read_b128 v[156:159], v251 offset:52224
	ds_read_b128 v[160:163], v251 offset:53248
	ds_read_b128 v[164:167], v251 offset:54272
	ds_read_b128 v[168:171], v251 offset:55296
	ds_read_b128 v[172:175], v251 offset:56320
	global_load_lds_dwordx4 v[194:195], off
	v_lshl_add_u64 v[194:195], v[216:217], 0, s[74:75]
	s_mov_b32 m0, s81
	s_nop 0
	global_load_lds_dwordx4 v[194:195], off
	s_barrier
; __device__ __forceinline__ unsigned cvt_pk_bf16(float lo, float hi) { unsigned r; asm volatile("s_nop 0\n\tv_cvt_pk_bf16_f32 %0, %1, %2\n\ts_nop 1" : "=v"(r) : "v"(lo), "v"(hi)); return r; }
; #define PG8_STAGE(bufoff, gbase, voff) do { _Pragma("unroll") for (int _i = 0; _i < 2; ++_i) \
;         __builtin_amdgcn_global_load_lds((const unsigned*)((const char*)(gbase) + (voff)[_i]), (PG8_LAS unsigned*)(lds + (bufoff) + ldsw + _i * 8192), 16, 0, 0); } while (0)
; #define PG8_LDA(dst, b, h) do { _Pragma("unroll") for (int m = 0; m < 4; ++m) _Pragma("unroll") for (int k = 0; k < 2; ++k) dst[m][k] = *(const PG8_LAS bf16x8*)(lds + PG8_SA(b, h) + aoff + m * 2048 + k * 1024); } while (0)
; #define PG8_WAIT_V(n) asm volatile("s_waitcnt vmcnt(" #n ")" ::: "memory")
; #define PG8_WAIT_L(n) asm volatile("s_waitcnt lgkmcnt(" #n ")" ::: "memory")
; #define PG8_BAR __builtin_amdgcn_s_barrier()
; #define PG8_SCHED __builtin_amdgcn_sched_barrier(0)
; template <class Epi, class Sched>
; __device__ __forceinline__ void gemm_phase(PG8_LAS unsigned char* lds, const Gemm g, const Sched& S, const Epi& E, int tid_in) {
;     ...
;             PG8_LDA(At, 1, 1); PG8_STAGE(PG8_SA(1, 0), a3, voffA);
;             PG8_BAR; PG8_WAIT_L(0); PG8_MMA(1, 0, At, B0); PG8_BAR; PG8_SCHED;
;             PG8_STAGE(PG8_SB(1, 1), b3 + hstep, voffB);
;             PG8_WAIT_V(6); PG8_BAR; PG8_MMA(1, 1, At, B1); PG8_BAR;
;     __device__ __forceinline__ void operator()(f32x4 (&acc)[2][2][4][2], const Unit& u, int wr, int wc, int fr, int fq) const {
;     ...
; #pragma unroll
;             for (int bj = 0; bj < 2; ++bj) { const int col = (u.pn - 12) * 256 + bj * 128 + c8;
;                 const f32x4 b0 = *(const f32x4*)(b_gate + col), b1 = *(const f32x4*)(b_gate + col + 4);
; #pragma unroll
;                 for (int ai = 0; ai < 2; ++ai)
; #pragma unroll
;                     for (int m = 0; m < 4; ++m) { const f32x4 v0 = acc[ai][bj][m][0] + b0, v1 = acc[ai][bj][m][1] + b1;
;                         u32x4 w; w.x = cvt_pk_bf16(sigmoidf_(v0[0]), sigmoidf_(v0[1])); w.y = cvt_pk_bf16(sigmoidf_(v0[2]), sigmoidf_(v0[3]));
;                         w.z = cvt_pk_bf16(sigmoidf_(v1[0]), sigmoidf_(v1[1])); w.w = cvt_pk_bf16(sigmoidf_(v1[2]), sigmoidf_(v1[3]));
;                         *(u32x4*)(gates + (size_t)(row0 + ai * 128 + m * 16) * 2048 + col) = w; } }
	s_waitcnt lgkmcnt(0)
	s_setprio 1
	s_waitcnt lgkmcnt(0)
	v_mfma_f32_16x16x32_bf16 v[60:63], v[128:131], v[144:147], v[60:63]
	v_mfma_f32_16x16x32_bf16 v[56:59], v[136:139], v[144:147], v[56:59]
	v_mfma_f32_16x16x32_bf16 v[44:47], v[128:131], v[152:155], v[44:47]
	v_mfma_f32_16x16x32_bf16 v[40:43], v[136:139], v[152:155], v[40:43]
	v_mfma_f32_16x16x32_bf16 v[28:31], v[128:131], v[160:163], v[28:31]
	v_mfma_f32_16x16x32_bf16 v[24:27], v[136:139], v[160:163], v[24:27]
	v_mfma_f32_16x16x32_bf16 v[12:15], v[128:131], v[168:171], v[12:15]
	v_mfma_f32_16x16x32_bf16 v[8:11], v[136:139], v[168:171], v[8:11]
	v_mfma_f32_16x16x32_bf16 v[60:63], v[132:135], v[148:151], v[60:63]
	v_mfma_f32_16x16x32_bf16 v[56:59], v[140:143], v[148:151], v[56:59]
	v_mfma_f32_16x16x32_bf16 v[44:47], v[132:135], v[156:159], v[44:47]
	v_mfma_f32_16x16x32_bf16 v[40:43], v[140:143], v[156:159], v[40:43]
	v_mfma_f32_16x16x32_bf16 v[28:31], v[132:135], v[164:167], v[28:31]
	v_mfma_f32_16x16x32_bf16 v[24:27], v[140:143], v[164:167], v[24:27]
	v_mfma_f32_16x16x32_bf16 v[12:15], v[132:135], v[172:175], v[12:15]
	v_mfma_f32_16x16x32_bf16 v[8:11], v[140:143], v[172:175], v[8:11]
	s_setprio 0
	s_barrier
	s_add_u32 s28, s28, 0x40080
	s_addc_u32 s29, s29, 0
	s_add_i32 s30, s30, s72
	v_lshl_add_u64 v[128:129], s[28:29], 0, v[202:203]
	s_mov_b32 m0, s30
	s_nop 0
	global_load_lds_dwordx4 v[128:129], off
	v_lshl_add_u64 v[128:129], s[28:29], 0, v[206:207]
	s_add_i32 m0, s30, 0x2000
	s_nop 0
	global_load_lds_dwordx4 v[128:129], off
	s_waitcnt vmcnt(6)
	s_barrier
	s_setprio 1
	v_mfma_f32_16x16x32_bf16 v[52:55], v[176:179], v[144:147], v[52:55]
	v_mfma_f32_16x16x32_bf16 v[48:51], v[184:187], v[144:147], v[48:51]
	v_mfma_f32_16x16x32_bf16 v[36:39], v[176:179], v[152:155], v[36:39]
	v_mfma_f32_16x16x32_bf16 v[32:35], v[184:187], v[152:155], v[32:35]
	v_mfma_f32_16x16x32_bf16 v[20:23], v[176:179], v[160:163], v[20:23]
	v_mfma_f32_16x16x32_bf16 v[16:19], v[184:187], v[160:163], v[16:19]
	v_mfma_f32_16x16x32_bf16 v[4:7], v[176:179], v[168:171], v[4:7]
	v_mfma_f32_16x16x32_bf16 v[0:3], v[184:187], v[168:171], v[0:3]
	v_mfma_f32_16x16x32_bf16 v[52:55], v[180:183], v[148:151], v[52:55]
	v_mfma_f32_16x16x32_bf16 v[48:51], v[188:191], v[148:151], v[48:51]
	v_mfma_f32_16x16x32_bf16 v[36:39], v[180:183], v[156:159], v[36:39]
	v_mfma_f32_16x16x32_bf16 v[32:35], v[188:191], v[156:159], v[32:35]
	v_mfma_f32_16x16x32_bf16 v[20:23], v[180:183], v[164:167], v[20:23]
	v_mfma_f32_16x16x32_bf16 v[16:19], v[188:191], v[164:167], v[16:19]
	v_mfma_f32_16x16x32_bf16 v[4:7], v[180:183], v[172:175], v[4:7]
	v_mfma_f32_16x16x32_bf16 v[0:3], v[188:191], v[172:175], v[0:3]
	s_setprio 0
	s_add_i32 s37, s37, 2
	s_add_u32 s26, s26, 0x100
	s_addc_u32 s27, s27, 0
	s_add_u32 s33, s33, 0x100
	s_addc_u32 s36, s36, 0
	s_cmp_gt_u32 s37, 13
	s_barrier
	s_cbranch_scc0 .LBB0_388
	v_lshl_add_u32 v214, s0, 8, v209
	s_cmp_gt_i32 s24, 7
	s_mov_b64 s[0:1], -1
	s_cbranch_scc0 .LBB0_395
	s_lshl_b32 s17, s24, 8
	s_cmp_lt_u32 s24, 12
	s_cbranch_scc1 .LBB0_392
	v_or_b32_e32 v128, 0xfffff400, v208
	v_add_u32_e32 v140, s17, v128
	v_readlane_b32 s48, v255, 19
	v_ashrrev_i32_e32 v141, 31, v140
	v_readlane_b32 s49, v255, 20
	v_ashrrev_i32_e32 v215, 31, v214
	v_lshlrev_b64 v[146:147], 1, v[140:141]
	v_lshl_add_u64 v[132:133], v[140:141], 2, s[48:49]
	global_load_dwordx4 v[128:131], v[132:133], off offset:16
	s_nop 0
	global_load_dwordx4 v[132:135], v[132:133], off
	s_mov_b64 s[0:1], 0x80000
	v_or_b32_e32 v140, 0x80, v140
	v_lshl_add_u64 v[162:163], v[140:141], 2, s[48:49]
	global_load_dwordx4 v[164:167], v[162:163], off offset:16
	global_load_dwordx4 v[168:171], v[162:163], off
	v_readlane_b32 s50, v255, 21
	v_readlane_b32 s51, v255, 22
	v_readlane_b32 s52, v255, 23
	v_readlane_b32 s53, v255, 24
	v_readlane_b32 s54, v255, 25
	v_readlane_b32 s55, v255, 26
	s_waitcnt vmcnt(2)
	v_pk_add_f32 v[144:145], v[120:121], v[128:129]
	v_pk_add_f32 v[136:137], v[124:125], v[132:133]
	v_pk_add_f32 v[138:139], v[126:127], v[134:135]
	v_mul_f32_e32 v136, 0xbfb8aa3b, v136
	v_mul_f32_e32 v137, 0xbfb8aa3b, v137
	v_exp_f32_e32 v136, v136
	v_exp_f32_e32 v137, v137
	v_pk_add_f32 v[142:143], v[122:123], v[130:131]
	v_pk_add_f32 v[148:149], v[104:105], v[128:129]
	v_add_f32_e32 v136, 1.0, v136
	v_add_f32_e32 v137, 1.0, v137
	v_rcp_f32_e32 v136, v136
	v_rcp_f32_e32 v137, v137
	s_nop 0
	v_cvt_pk_bf16_f32 v136, v136, v137
	v_mul_f32_e32 v137, 0xbfb8aa3b, v138
	v_mul_f32_e32 v138, 0xbfb8aa3b, v139
	v_exp_f32_e32 v137, v137
	v_exp_f32_e32 v138, v138
	v_mul_f32_e32 v139, 0xbfb8aa3b, v145
	v_exp_f32_e32 v139, v139
	v_add_f32_e32 v137, 1.0, v137
	v_add_f32_e32 v138, 1.0, v138
	v_rcp_f32_e32 v137, v137
	v_rcp_f32_e32 v138, v138
	s_nop 0
	v_cvt_pk_bf16_f32 v137, v137, v138
	v_mul_f32_e32 v138, 0xbfb8aa3b, v144
	v_exp_f32_e32 v138, v138
	v_add_f32_e32 v139, 1.0, v139
	v_rcp_f32_e32 v139, v139
	v_pk_add_f32 v[150:151], v[88:89], v[128:129]
	v_add_f32_e32 v138, 1.0, v138
	v_rcp_f32_e32 v138, v138
	s_nop 0
	v_cvt_pk_bf16_f32 v138, v138, v139
	v_mul_f32_e32 v139, 0xbfb8aa3b, v142
	v_mul_f32_e32 v142, 0xbfb8aa3b, v143
	v_exp_f32_e32 v139, v139
	v_exp_f32_e32 v142, v142
	v_pk_add_f32 v[152:153], v[90:91], v[130:131]
	v_pk_add_f32 v[154:155], v[58:59], v[130:131]
	v_add_f32_e32 v139, 1.0, v139
	v_add_f32_e32 v142, 1.0, v142
	v_rcp_f32_e32 v139, v139
	v_rcp_f32_e32 v142, v142
	s_nop 0
	v_cvt_pk_bf16_f32 v139, v139, v142
	v_lshlrev_b64 v[142:143], 12, v[214:215]
	v_lshl_add_u64 v[142:143], s[14:15], 0, v[142:143]
	v_lshl_add_u64 v[144:145], v[142:143], 0, v[146:147]
	global_store_dwordx4 v[144:145], v[136:139], off
	v_pk_add_f32 v[144:145], v[106:107], v[130:131]
; __device__ __forceinline__ unsigned cvt_pk_bf16(float lo, float hi) { unsigned r; asm volatile("s_nop 0\n\tv_cvt_pk_bf16_f32 %0, %1, %2\n\ts_nop 1" : "=v"(r) : "v"(lo), "v"(hi)); return r; }
; __device__ __forceinline__ float sigmoidf_(float x) { return __builtin_amdgcn_rcpf(1.f + __expf(-x)); }
;     __device__ __forceinline__ void operator()(f32x4 (&acc)[2][2][4][2], const Unit& u, int wr, int wc, int fr, int fq) const {
;     ...
;                 for (int ai = 0; ai < 2; ++ai)
; #pragma unroll
;                     for (int m = 0; m < 4; ++m) { const f32x4 v0 = acc[ai][bj][m][0] + b0, v1 = acc[ai][bj][m][1] + b1;
;                         u32x4 w; w.x = cvt_pk_bf16(sigmoidf_(v0[0]), sigmoidf_(v0[1])); w.y = cvt_pk_bf16(sigmoidf_(v0[2]), sigmoidf_(v0[3]));
;                         w.z = cvt_pk_bf16(sigmoidf_(v1[0]), sigmoidf_(v1[1])); w.w = cvt_pk_bf16(sigmoidf_(v1[2]), sigmoidf_(v1[3]));
;                         *(u32x4*)(gates + (size_t)(row0 + ai * 128 + m * 16) * 2048 + col) = w; } }
	v_pk_add_f32 v[156:157], v[42:43], v[130:131]
	v_pk_add_f32 v[136:137], v[108:109], v[132:133]
	v_pk_add_f32 v[138:139], v[110:111], v[134:135]
	v_mul_f32_e32 v136, 0xbfb8aa3b, v136
	v_mul_f32_e32 v137, 0xbfb8aa3b, v137
	v_exp_f32_e32 v136, v136
	v_exp_f32_e32 v137, v137
	v_mul_f32_e32 v141, 0xbfb8aa3b, v145
	v_exp_f32_e32 v141, v141
	v_add_f32_e32 v136, 1.0, v136
	v_add_f32_e32 v137, 1.0, v137
	v_rcp_f32_e32 v136, v136
	v_rcp_f32_e32 v137, v137
	s_nop 0
	v_cvt_pk_bf16_f32 v136, v136, v137
	v_mul_f32_e32 v137, 0xbfb8aa3b, v138
	v_mul_f32_e32 v138, 0xbfb8aa3b, v139
	v_exp_f32_e32 v137, v137
	v_exp_f32_e32 v138, v138
	v_mul_f32_e32 v139, 0xbfb8aa3b, v149
	v_exp_f32_e32 v139, v139
	v_add_f32_e32 v137, 1.0, v137
	v_add_f32_e32 v138, 1.0, v138
	v_rcp_f32_e32 v137, v137
	v_rcp_f32_e32 v138, v138
	s_nop 0
	v_cvt_pk_bf16_f32 v137, v137, v138
	v_mul_f32_e32 v138, 0xbfb8aa3b, v148
	v_exp_f32_e32 v138, v138
	v_add_f32_e32 v139, 1.0, v139
	v_rcp_f32_e32 v139, v139
	v_add_f32_e32 v141, 1.0, v141
	v_add_f32_e32 v138, 1.0, v138
	v_rcp_f32_e32 v138, v138
	s_nop 0
	v_cvt_pk_bf16_f32 v138, v138, v139
	v_mul_f32_e32 v139, 0xbfb8aa3b, v144
	v_exp_f32_e32 v139, v139
	v_or_b32_e32 v144, 16, v214
	v_ashrrev_i32_e32 v145, 31, v144
	v_lshlrev_b64 v[144:145], 12, v[144:145]
	v_add_f32_e32 v139, 1.0, v139
	v_lshl_add_u64 v[144:145], s[14:15], 0, v[144:145]
	v_rcp_f32_e32 v139, v139
	v_lshl_add_u64 v[148:149], v[144:145], 0, v[146:147]
	v_rcp_f32_e32 v141, v141
	s_nop 0
	v_cvt_pk_bf16_f32 v139, v139, v141
	global_store_dwordx4 v[148:149], v[136:139], off
	v_pk_add_f32 v[158:159], v[26:27], v[130:131]
	s_nop 0
	v_pk_add_f32 v[136:137], v[94:95], v[134:135]
	v_pk_add_f32 v[138:139], v[92:93], v[132:133]
	v_mul_f32_e32 v136, 0xbfb8aa3b, v136
	v_mul_f32_e32 v138, 0xbfb8aa3b, v138
	v_mul_f32_e32 v139, 0xbfb8aa3b, v139
	v_exp_f32_e32 v136, v136
	v_mul_f32_e32 v137, 0xbfb8aa3b, v137
	v_exp_f32_e32 v138, v138
	v_exp_f32_e32 v139, v139
	v_exp_f32_e32 v137, v137
	v_add_f32_e32 v136, 1.0, v136
	v_add_f32_e32 v138, 1.0, v138
	v_add_f32_e32 v139, 1.0, v139
	v_rcp_f32_e32 v136, v136
	v_add_f32_e32 v137, 1.0, v137
	v_rcp_f32_e32 v138, v138
	v_rcp_f32_e32 v139, v139
	s_nop 0
	v_cvt_pk_bf16_f32 v148, v138, v139
	v_rcp_f32_e32 v137, v137
	s_nop 0
	v_cvt_pk_bf16_f32 v149, v136, v137
	v_mul_f32_e32 v136, 0xbfb8aa3b, v150
	v_exp_f32_e32 v136, v136
	v_mul_f32_e32 v137, 0xbfb8aa3b, v151
	v_exp_f32_e32 v137, v137
	v_add_f32_e32 v136, 1.0, v136
	v_rcp_f32_e32 v136, v136
	v_add_f32_e32 v137, 1.0, v137
	v_rcp_f32_e32 v137, v137
	s_nop 0
	v_cvt_pk_bf16_f32 v150, v136, v137
	v_mul_f32_e32 v136, 0xbfb8aa3b, v152
	v_exp_f32_e32 v136, v136
	v_mul_f32_e32 v137, 0xbfb8aa3b, v153
	v_exp_f32_e32 v137, v137
	v_pk_add_f32 v[152:153], v[74:75], v[130:131]
	v_add_f32_e32 v136, 1.0, v136
	v_rcp_f32_e32 v136, v136
	v_add_f32_e32 v137, 1.0, v137
	v_rcp_f32_e32 v137, v137
	s_nop 0
	v_cvt_pk_bf16_f32 v151, v136, v137
	v_or_b32_e32 v136, 32, v214
	v_ashrrev_i32_e32 v137, 31, v136
	v_lshlrev_b64 v[136:137], 12, v[136:137]
	v_lshl_add_u64 v[136:137], s[14:15], 0, v[136:137]
	v_lshl_add_u64 v[138:139], v[136:137], 0, v[146:147]
	global_store_dwordx4 v[138:139], v[148:151], off
	v_pk_add_f32 v[138:139], v[78:79], v[134:135]
	s_nop 0
	v_pk_add_f32 v[148:149], v[76:77], v[132:133]
	v_mul_f32_e32 v138, 0xbfb8aa3b, v138
	v_mul_f32_e32 v141, 0xbfb8aa3b, v148
	v_mul_f32_e32 v148, 0xbfb8aa3b, v149
	v_exp_f32_e32 v148, v148
	v_exp_f32_e32 v138, v138
	v_mul_f32_e32 v139, 0xbfb8aa3b, v139
	v_exp_f32_e32 v141, v141
	v_exp_f32_e32 v139, v139
	v_add_f32_e32 v148, 1.0, v148
	v_add_f32_e32 v138, 1.0, v138
	v_pk_add_f32 v[150:151], v[72:73], v[128:129]
	v_add_f32_e32 v141, 1.0, v141
	v_rcp_f32_e32 v148, v148
	v_rcp_f32_e32 v138, v138
	v_add_f32_e32 v139, 1.0, v139
	v_rcp_f32_e32 v141, v141
	s_nop 0
	v_cvt_pk_bf16_f32 v148, v141, v148
	v_rcp_f32_e32 v139, v139
	s_nop 0
	v_cvt_pk_bf16_f32 v149, v138, v139
	v_mul_f32_e32 v138, 0xbfb8aa3b, v150
	v_exp_f32_e32 v138, v138
	v_mul_f32_e32 v139, 0xbfb8aa3b, v151
	v_exp_f32_e32 v139, v139
	v_add_f32_e32 v138, 1.0, v138
	v_rcp_f32_e32 v138, v138
	v_add_f32_e32 v139, 1.0, v139
	v_rcp_f32_e32 v139, v139
	s_nop 0
	v_cvt_pk_bf16_f32 v150, v138, v139
	v_mul_f32_e32 v138, 0xbfb8aa3b, v152
	v_exp_f32_e32 v138, v138
	v_mul_f32_e32 v139, 0xbfb8aa3b, v153
	v_exp_f32_e32 v139, v139
	v_add_f32_e32 v138, 1.0, v138
	v_rcp_f32_e32 v138, v138
	v_add_f32_e32 v139, 1.0, v139
	v_rcp_f32_e32 v139, v139
	s_nop 0
	v_cvt_pk_bf16_f32 v151, v138, v139
	v_or_b32_e32 v138, 48, v214
	v_ashrrev_i32_e32 v139, 31, v138
	v_lshlrev_b64 v[138:139], 12, v[138:139]
	v_lshl_add_u64 v[138:139], s[14:15], 0, v[138:139]
	v_lshl_add_u64 v[152:153], v[138:139], 0, v[146:147]
	global_store_dwordx4 v[152:153], v[148:151], off
	v_pk_add_f32 v[152:153], v[56:57], v[128:129]
	s_nop 0
	v_pk_add_f32 v[150:151], v[60:61], v[132:133]
	v_pk_add_f32 v[148:149], v[62:63], v[134:135]
	v_mul_f32_e32 v141, 0xbfb8aa3b, v150
	v_mul_f32_e32 v150, 0xbfb8aa3b, v151
	v_exp_f32_e32 v141, v141
	v_exp_f32_e32 v150, v150
	v_add_f32_e32 v141, 1.0, v141
	v_add_f32_e32 v150, 1.0, v150
	v_rcp_f32_e32 v141, v141
	v_rcp_f32_e32 v150, v150
	s_nop 0
	v_cvt_pk_bf16_f32 v150, v141, v150
	v_mul_f32_e32 v141, 0xbfb8aa3b, v148
	v_mul_f32_e32 v148, 0xbfb8aa3b, v149
	v_exp_f32_e32 v148, v148
	v_exp_f32_e32 v141, v141
	v_add_f32_e32 v148, 1.0, v148
	v_add_f32_e32 v141, 1.0, v141
	v_rcp_f32_e32 v148, v148
	v_rcp_f32_e32 v141, v141
	s_nop 0
	v_cvt_pk_bf16_f32 v151, v141, v148
	v_mul_f32_e32 v148, 0xbfb8aa3b, v153
	v_mul_f32_e32 v141, 0xbfb8aa3b, v152
	v_exp_f32_e32 v148, v148
	v_exp_f32_e32 v141, v141
	v_add_f32_e32 v148, 1.0, v148
	v_add_f32_e32 v141, 1.0, v141
; __device__ __forceinline__ unsigned cvt_pk_bf16(float lo, float hi) { unsigned r; asm volatile("s_nop 0\n\tv_cvt_pk_bf16_f32 %0, %1, %2\n\ts_nop 1" : "=v"(r) : "v"(lo), "v"(hi)); return r; }
; __device__ __forceinline__ float sigmoidf_(float x) { return __builtin_amdgcn_rcpf(1.f + __expf(-x)); }
;     __device__ __forceinline__ void operator()(f32x4 (&acc)[2][2][4][2], const Unit& u, int wr, int wc, int fr, int fq) const {
;     ...
; #pragma unroll
;             for (int bj = 0; bj < 2; ++bj) { const int col = (u.pn - 12) * 256 + bj * 128 + c8;
;                 const f32x4 b0 = *(const f32x4*)(b_gate + col), b1 = *(const f32x4*)(b_gate + col + 4);
; #pragma unroll
;                 for (int ai = 0; ai < 2; ++ai)
; #pragma unroll
;                     for (int m = 0; m < 4; ++m) { const f32x4 v0 = acc[ai][bj][m][0] + b0, v1 = acc[ai][bj][m][1] + b1;
;                         u32x4 w; w.x = cvt_pk_bf16(sigmoidf_(v0[0]), sigmoidf_(v0[1])); w.y = cvt_pk_bf16(sigmoidf_(v0[2]), sigmoidf_(v0[3]));
;                         w.z = cvt_pk_bf16(sigmoidf_(v1[0]), sigmoidf_(v1[1])); w.w = cvt_pk_bf16(sigmoidf_(v1[2]), sigmoidf_(v1[3]));
;                         *(u32x4*)(gates + (size_t)(row0 + ai * 128 + m * 16) * 2048 + col) = w; } }
	v_rcp_f32_e32 v148, v148
	v_rcp_f32_e32 v141, v141
	s_nop 0
	v_cvt_pk_bf16_f32 v152, v141, v148
	v_mul_f32_e32 v148, 0xbfb8aa3b, v155
	v_mul_f32_e32 v141, 0xbfb8aa3b, v154
	v_exp_f32_e32 v148, v148
	v_exp_f32_e32 v141, v141
	v_add_f32_e32 v148, 1.0, v148
	v_add_f32_e32 v141, 1.0, v141
	v_rcp_f32_e32 v148, v148
	v_rcp_f32_e32 v141, v141
	s_nop 0
	v_cvt_pk_bf16_f32 v153, v141, v148
	v_lshl_add_u64 v[148:149], v[142:143], 0, s[0:1]
	v_lshl_add_u64 v[154:155], v[148:149], 0, v[146:147]
	global_store_dwordx4 v[154:155], v[150:153], off
	v_pk_add_f32 v[154:155], v[40:41], v[128:129]
	s_mov_b64 s[0:1], 0x90000
	v_pk_add_f32 v[152:153], v[44:45], v[132:133]
	v_pk_add_f32 v[150:151], v[46:47], v[134:135]
	v_mul_f32_e32 v141, 0xbfb8aa3b, v152
	v_mul_f32_e32 v152, 0xbfb8aa3b, v153
	v_exp_f32_e32 v141, v141
	v_exp_f32_e32 v152, v152
	v_add_f32_e32 v141, 1.0, v141
	v_add_f32_e32 v152, 1.0, v152
	v_rcp_f32_e32 v141, v141
	v_rcp_f32_e32 v152, v152
	s_nop 0
	v_cvt_pk_bf16_f32 v152, v141, v152
	v_mul_f32_e32 v141, 0xbfb8aa3b, v150
	v_mul_f32_e32 v150, 0xbfb8aa3b, v151
	v_exp_f32_e32 v150, v150
	v_exp_f32_e32 v141, v141
	v_add_f32_e32 v150, 1.0, v150
	v_add_f32_e32 v141, 1.0, v141
	v_rcp_f32_e32 v150, v150
	v_rcp_f32_e32 v141, v141
	s_nop 0
	v_cvt_pk_bf16_f32 v153, v141, v150
	v_mul_f32_e32 v150, 0xbfb8aa3b, v155
	v_mul_f32_e32 v141, 0xbfb8aa3b, v154
	v_exp_f32_e32 v150, v150
	v_exp_f32_e32 v141, v141
	v_add_f32_e32 v150, 1.0, v150
	v_add_f32_e32 v141, 1.0, v141
	v_rcp_f32_e32 v150, v150
	v_rcp_f32_e32 v141, v141
	s_nop 0
	v_cvt_pk_bf16_f32 v154, v141, v150
	v_mul_f32_e32 v150, 0xbfb8aa3b, v157
	v_mul_f32_e32 v141, 0xbfb8aa3b, v156
	v_exp_f32_e32 v150, v150
	v_exp_f32_e32 v141, v141
	v_add_f32_e32 v150, 1.0, v150
	v_add_f32_e32 v141, 1.0, v141
	v_rcp_f32_e32 v150, v150
	v_rcp_f32_e32 v141, v141
	s_nop 0
	v_cvt_pk_bf16_f32 v155, v141, v150
	v_lshl_add_u64 v[150:151], v[142:143], 0, s[0:1]
	v_lshl_add_u64 v[156:157], v[150:151], 0, v[146:147]
	global_store_dwordx4 v[156:157], v[152:155], off
	v_pk_add_f32 v[156:157], v[24:25], v[128:129]
	s_mov_b64 s[0:1], 0xa0000
	v_pk_add_f32 v[154:155], v[28:29], v[132:133]
	v_pk_add_f32 v[152:153], v[30:31], v[134:135]
	v_mul_f32_e32 v141, 0xbfb8aa3b, v154
	v_mul_f32_e32 v154, 0xbfb8aa3b, v155
	v_exp_f32_e32 v141, v141
	v_exp_f32_e32 v154, v154
	v_pk_add_f32 v[132:133], v[12:13], v[132:133]
	v_pk_add_f32 v[134:135], v[14:15], v[134:135]
	v_add_f32_e32 v141, 1.0, v141
	v_add_f32_e32 v154, 1.0, v154
	v_rcp_f32_e32 v141, v141
	v_rcp_f32_e32 v154, v154
	s_nop 0
	v_cvt_pk_bf16_f32 v154, v141, v154
	v_mul_f32_e32 v141, 0xbfb8aa3b, v152
	v_mul_f32_e32 v152, 0xbfb8aa3b, v153
	v_exp_f32_e32 v152, v152
	v_exp_f32_e32 v141, v141
	v_add_f32_e32 v152, 1.0, v152
	v_add_f32_e32 v141, 1.0, v141
	v_rcp_f32_e32 v152, v152
	v_rcp_f32_e32 v141, v141
	s_nop 0
	v_cvt_pk_bf16_f32 v155, v141, v152
	v_mul_f32_e32 v152, 0xbfb8aa3b, v157
	v_mul_f32_e32 v141, 0xbfb8aa3b, v156
	v_exp_f32_e32 v152, v152
	v_exp_f32_e32 v141, v141
	v_add_f32_e32 v152, 1.0, v152
	v_add_f32_e32 v141, 1.0, v141
	v_rcp_f32_e32 v152, v152
	v_rcp_f32_e32 v141, v141
	s_nop 0
	v_cvt_pk_bf16_f32 v156, v141, v152
	v_mul_f32_e32 v152, 0xbfb8aa3b, v159
	v_mul_f32_e32 v141, 0xbfb8aa3b, v158
	v_exp_f32_e32 v152, v152
	v_exp_f32_e32 v141, v141
	v_add_f32_e32 v152, 1.0, v152
	v_add_f32_e32 v141, 1.0, v141
	v_rcp_f32_e32 v152, v152
	v_rcp_f32_e32 v141, v141
	s_nop 0
	v_cvt_pk_bf16_f32 v157, v141, v152
	v_lshl_add_u64 v[152:153], v[142:143], 0, s[0:1]
	v_lshl_add_u64 v[158:159], v[152:153], 0, v[146:147]
	global_store_dwordx4 v[158:159], v[154:157], off
	s_mov_b64 s[0:1], 0xb0000
	v_ashrrev_i32_e32 v141, 31, v140
	v_pk_add_f32 v[154:155], v[10:11], v[130:131]
	v_pk_add_f32 v[130:131], v[8:9], v[128:129]
	v_mul_f32_e32 v128, 0xbfb8aa3b, v132
	v_mul_f32_e32 v129, 0xbfb8aa3b, v133
	v_exp_f32_e32 v128, v128
	v_exp_f32_e32 v129, v129
	v_mul_f32_e32 v132, 0xbfb8aa3b, v135
	v_mul_f32_e32 v130, 0xbfb8aa3b, v130
	v_add_f32_e32 v128, 1.0, v128
	v_add_f32_e32 v129, 1.0, v129
	v_rcp_f32_e32 v128, v128
	v_rcp_f32_e32 v129, v129
	s_nop 0
	v_cvt_pk_bf16_f32 v128, v128, v129
	v_mul_f32_e32 v129, 0xbfb8aa3b, v134
	v_mul_f32_e32 v131, 0xbfb8aa3b, v131
	v_exp_f32_e32 v129, v129
	v_exp_f32_e32 v132, v132
	v_exp_f32_e32 v130, v130
	v_exp_f32_e32 v131, v131
	v_add_f32_e32 v129, 1.0, v129
	v_add_f32_e32 v132, 1.0, v132
	v_add_f32_e32 v130, 1.0, v130
	v_add_f32_e32 v131, 1.0, v131
	v_rcp_f32_e32 v129, v129
	v_rcp_f32_e32 v132, v132
	v_rcp_f32_e32 v130, v130
	v_rcp_f32_e32 v131, v131
	s_nop 0
	v_cvt_pk_bf16_f32 v129, v129, v132
	v_cvt_pk_bf16_f32 v130, v130, v131
	v_mul_f32_e32 v131, 0xbfb8aa3b, v154
	v_mul_f32_e32 v132, 0xbfb8aa3b, v155
	v_exp_f32_e32 v131, v131
	v_exp_f32_e32 v132, v132
	v_lshl_add_u64 v[154:155], v[142:143], 0, s[0:1]
	s_mov_b64 s[0:1], 0
	v_add_f32_e32 v131, 1.0, v131
	v_add_f32_e32 v132, 1.0, v132
	v_rcp_f32_e32 v131, v131
	v_rcp_f32_e32 v132, v132
	s_nop 0
	v_cvt_pk_bf16_f32 v131, v131, v132
	v_lshl_add_u64 v[132:133], v[154:155], 0, v[146:147]
	global_store_dwordx4 v[132:133], v[128:131], off
	s_nop 0
	v_lshlrev_b64 v[140:141], 1, v[140:141]
	v_lshl_add_u64 v[142:143], v[142:143], 0, v[140:141]
	v_lshl_add_u64 v[136:137], v[136:137], 0, v[140:141]
	s_waitcnt vmcnt(8)
; __device__ __forceinline__ unsigned cvt_pk_bf16(float lo, float hi) { unsigned r; asm volatile("s_nop 0\n\tv_cvt_pk_bf16_f32 %0, %1, %2\n\ts_nop 1" : "=v"(r) : "v"(lo), "v"(hi)); return r; }
; __device__ __forceinline__ float sigmoidf_(float x) { return __builtin_amdgcn_rcpf(1.f + __expf(-x)); }
;     __device__ __forceinline__ void operator()(f32x4 (&acc)[2][2][4][2], const Unit& u, int wr, int wc, int fr, int fq) const {
;     ...
;                 for (int ai = 0; ai < 2; ++ai)
; #pragma unroll
;                     for (int m = 0; m < 4; ++m) { const f32x4 v0 = acc[ai][bj][m][0] + b0, v1 = acc[ai][bj][m][1] + b1;
;                         u32x4 w; w.x = cvt_pk_bf16(sigmoidf_(v0[0]), sigmoidf_(v0[1])); w.y = cvt_pk_bf16(sigmoidf_(v0[2]), sigmoidf_(v0[3]));
;                         w.z = cvt_pk_bf16(sigmoidf_(v1[0]), sigmoidf_(v1[1])); w.w = cvt_pk_bf16(sigmoidf_(v1[2]), sigmoidf_(v1[3]));
;                         *(u32x4*)(gates + (size_t)(row0 + ai * 128 + m * 16) * 2048 + col) = w; } }
	v_pk_add_f32 v[158:159], v[112:113], v[164:165]
	v_pk_add_f32 v[146:147], v[118:119], v[170:171]
	v_pk_add_f32 v[156:157], v[116:117], v[168:169]
	v_mul_f32_e32 v146, 0xbfb8aa3b, v146
	v_mul_f32_e32 v156, 0xbfb8aa3b, v156
	v_mul_f32_e32 v157, 0xbfb8aa3b, v157
	v_mul_f32_e32 v147, 0xbfb8aa3b, v147
	v_exp_f32_e32 v156, v156
	v_exp_f32_e32 v157, v157
	v_exp_f32_e32 v146, v146
	v_exp_f32_e32 v147, v147
	v_add_f32_e32 v156, 1.0, v156
	v_add_f32_e32 v157, 1.0, v157
	v_add_f32_e32 v146, 1.0, v146
	v_add_f32_e32 v147, 1.0, v147
	v_rcp_f32_e32 v156, v156
	v_rcp_f32_e32 v157, v157
	v_rcp_f32_e32 v146, v146
	v_rcp_f32_e32 v147, v147
	s_nop 0
	v_cvt_pk_bf16_f32 v156, v156, v157
	v_cvt_pk_bf16_f32 v157, v146, v147
	v_mul_f32_e32 v146, 0xbfb8aa3b, v158
	v_mul_f32_e32 v147, 0xbfb8aa3b, v159
	v_exp_f32_e32 v146, v146
	v_exp_f32_e32 v147, v147
	v_pk_add_f32 v[160:161], v[114:115], v[166:167]
	v_add_f32_e32 v146, 1.0, v146
	v_add_f32_e32 v147, 1.0, v147
	v_rcp_f32_e32 v146, v146
	v_rcp_f32_e32 v147, v147
	s_nop 0
	v_cvt_pk_bf16_f32 v158, v146, v147
	v_mul_f32_e32 v146, 0xbfb8aa3b, v160
	v_mul_f32_e32 v147, 0xbfb8aa3b, v161
	v_exp_f32_e32 v146, v146
	v_exp_f32_e32 v147, v147
	v_pk_add_f32 v[160:161], v[98:99], v[166:167]
	v_add_f32_e32 v146, 1.0, v146
	v_add_f32_e32 v147, 1.0, v147
	v_rcp_f32_e32 v146, v146
	v_rcp_f32_e32 v147, v147
	s_nop 0
	v_cvt_pk_bf16_f32 v159, v146, v147
	global_store_dwordx4 v[142:143], v[156:159], off
	v_pk_add_f32 v[142:143], v[102:103], v[170:171]
	v_pk_add_f32 v[146:147], v[100:101], v[168:169]
	v_mul_f32_e32 v142, 0xbfb8aa3b, v142
	v_mul_f32_e32 v143, 0xbfb8aa3b, v143
	v_mul_f32_e32 v146, 0xbfb8aa3b, v146
	v_mul_f32_e32 v147, 0xbfb8aa3b, v147
	v_exp_f32_e32 v142, v142
	v_exp_f32_e32 v143, v143
	v_exp_f32_e32 v146, v146
	v_exp_f32_e32 v147, v147
	v_add_f32_e32 v142, 1.0, v142
	v_add_f32_e32 v143, 1.0, v143
	v_pk_add_f32 v[158:159], v[96:97], v[164:165]
	v_add_f32_e32 v146, 1.0, v146
	v_add_f32_e32 v147, 1.0, v147
	v_rcp_f32_e32 v142, v142
	v_rcp_f32_e32 v143, v143
	v_rcp_f32_e32 v146, v146
	v_rcp_f32_e32 v147, v147
	s_nop 0
	v_cvt_pk_bf16_f32 v156, v146, v147
	v_cvt_pk_bf16_f32 v157, v142, v143
	v_mul_f32_e32 v142, 0xbfb8aa3b, v158
	v_mul_f32_e32 v143, 0xbfb8aa3b, v159
	v_exp_f32_e32 v142, v142
	v_exp_f32_e32 v143, v143
	v_pk_add_f32 v[146:147], v[82:83], v[166:167]
	v_add_f32_e32 v142, 1.0, v142
	v_add_f32_e32 v143, 1.0, v143
	v_rcp_f32_e32 v142, v142
	v_rcp_f32_e32 v143, v143
	s_nop 0
	v_cvt_pk_bf16_f32 v158, v142, v143
	v_mul_f32_e32 v142, 0xbfb8aa3b, v160
	v_mul_f32_e32 v143, 0xbfb8aa3b, v161
	v_exp_f32_e32 v142, v142
	v_exp_f32_e32 v143, v143
	v_add_f32_e32 v142, 1.0, v142
	v_add_f32_e32 v143, 1.0, v143
	v_rcp_f32_e32 v142, v142
	v_rcp_f32_e32 v143, v143
	s_nop 0
	v_cvt_pk_bf16_f32 v159, v142, v143
	v_lshl_add_u64 v[142:143], v[144:145], 0, v[140:141]
	global_store_dwordx4 v[142:143], v[156:159], off
	v_pk_add_f32 v[142:143], v[84:85], v[168:169]
	v_pk_add_f32 v[144:145], v[86:87], v[170:171]
	v_mul_f32_e32 v142, 0xbfb8aa3b, v142
	v_mul_f32_e32 v143, 0xbfb8aa3b, v143
	v_exp_f32_e32 v142, v142
	v_exp_f32_e32 v143, v143
	v_pk_add_f32 v[156:157], v[80:81], v[164:165]
	v_add_f32_e32 v142, 1.0, v142
	v_add_f32_e32 v143, 1.0, v143
	v_rcp_f32_e32 v142, v142
	v_rcp_f32_e32 v143, v143
	s_nop 0
	v_cvt_pk_bf16_f32 v142, v142, v143
	v_mul_f32_e32 v143, 0xbfb8aa3b, v144
	v_mul_f32_e32 v144, 0xbfb8aa3b, v145
	v_exp_f32_e32 v143, v143
	v_exp_f32_e32 v144, v144
	v_mul_f32_e32 v145, 0xbfb8aa3b, v157
	v_exp_f32_e32 v145, v145
	v_add_f32_e32 v143, 1.0, v143
	v_add_f32_e32 v144, 1.0, v144
	v_rcp_f32_e32 v143, v143
	v_rcp_f32_e32 v144, v144
	s_nop 0
	v_cvt_pk_bf16_f32 v143, v143, v144
	v_mul_f32_e32 v144, 0xbfb8aa3b, v156
	v_exp_f32_e32 v144, v144
	v_add_f32_e32 v145, 1.0, v145
	v_rcp_f32_e32 v145, v145
	v_add_f32_e32 v144, 1.0, v144
	v_rcp_f32_e32 v144, v144
	s_nop 0
	v_cvt_pk_bf16_f32 v144, v144, v145
	v_mul_f32_e32 v145, 0xbfb8aa3b, v146
	v_exp_f32_e32 v145, v145
	v_mul_f32_e32 v146, 0xbfb8aa3b, v147
	v_exp_f32_e32 v146, v146
	v_add_f32_e32 v145, 1.0, v145
	v_rcp_f32_e32 v145, v145
	v_add_f32_e32 v146, 1.0, v146
	v_rcp_f32_e32 v146, v146
	s_nop 0
	v_cvt_pk_bf16_f32 v145, v145, v146
	global_store_dwordx4 v[136:137], v[142:145], off
	v_pk_add_f32 v[136:137], v[70:71], v[170:171]
	v_pk_add_f32 v[146:147], v[66:67], v[166:167]
	v_pk_add_f32 v[142:143], v[68:69], v[168:169]
	v_mul_f32_e32 v136, 0xbfb8aa3b, v136
	v_mul_f32_e32 v142, 0xbfb8aa3b, v142
	v_mul_f32_e32 v143, 0xbfb8aa3b, v143
	v_mul_f32_e32 v137, 0xbfb8aa3b, v137
	v_exp_f32_e32 v142, v142
	v_exp_f32_e32 v143, v143
	v_exp_f32_e32 v136, v136
	v_exp_f32_e32 v137, v137
	v_add_f32_e32 v142, 1.0, v142
	v_add_f32_e32 v143, 1.0, v143
	v_add_f32_e32 v136, 1.0, v136
	v_add_f32_e32 v137, 1.0, v137
	v_pk_add_f32 v[144:145], v[64:65], v[164:165]
	v_rcp_f32_e32 v142, v142
	v_rcp_f32_e32 v143, v143
	v_rcp_f32_e32 v136, v136
	v_rcp_f32_e32 v137, v137
	s_nop 0
	v_cvt_pk_bf16_f32 v142, v142, v143
	v_cvt_pk_bf16_f32 v143, v136, v137
	v_mul_f32_e32 v136, 0xbfb8aa3b, v144
	v_mul_f32_e32 v137, 0xbfb8aa3b, v145
	v_exp_f32_e32 v136, v136
	v_exp_f32_e32 v137, v137
	v_add_f32_e32 v136, 1.0, v136
	v_add_f32_e32 v137, 1.0, v137
	v_rcp_f32_e32 v136, v136
	v_rcp_f32_e32 v137, v137
	s_nop 0
	v_cvt_pk_bf16_f32 v144, v136, v137
	v_mul_f32_e32 v136, 0xbfb8aa3b, v146
	v_mul_f32_e32 v137, 0xbfb8aa3b, v147
	v_exp_f32_e32 v136, v136
	v_exp_f32_e32 v137, v137
	v_add_f32_e32 v136, 1.0, v136
	v_add_f32_e32 v137, 1.0, v137
	v_rcp_f32_e32 v136, v136
	v_rcp_f32_e32 v137, v137
	s_nop 0
	v_cvt_pk_bf16_f32 v145, v136, v137
	v_lshl_add_u64 v[136:137], v[138:139], 0, v[140:141]
	global_store_dwordx4 v[136:137], v[142:145], off
; __device__ __forceinline__ unsigned cvt_pk_bf16(float lo, float hi) { unsigned r; asm volatile("s_nop 0\n\tv_cvt_pk_bf16_f32 %0, %1, %2\n\ts_nop 1" : "=v"(r) : "v"(lo), "v"(hi)); return r; }
; __device__ __forceinline__ float sigmoidf_(float x) { return __builtin_amdgcn_rcpf(1.f + __expf(-x)); }
;     __device__ __forceinline__ void operator()(f32x4 (&acc)[2][2][4][2], const Unit& u, int wr, int wc, int fr, int fq) const {
;     ...
;                 for (int ai = 0; ai < 2; ++ai)
; #pragma unroll
;                     for (int m = 0; m < 4; ++m) { const f32x4 v0 = acc[ai][bj][m][0] + b0, v1 = acc[ai][bj][m][1] + b1;
;                         u32x4 w; w.x = cvt_pk_bf16(sigmoidf_(v0[0]), sigmoidf_(v0[1])); w.y = cvt_pk_bf16(sigmoidf_(v0[2]), sigmoidf_(v0[3]));
;                         w.z = cvt_pk_bf16(sigmoidf_(v1[0]), sigmoidf_(v1[1])); w.w = cvt_pk_bf16(sigmoidf_(v1[2]), sigmoidf_(v1[3]));
;                         *(u32x4*)(gates + (size_t)(row0 + ai * 128 + m * 16) * 2048 + col) = w; } }
	v_pk_add_f32 v[136:137], v[52:53], v[168:169]
	v_pk_add_f32 v[138:139], v[54:55], v[170:171]
	v_mul_f32_e32 v136, 0xbfb8aa3b, v136
	v_mul_f32_e32 v137, 0xbfb8aa3b, v137
	v_exp_f32_e32 v136, v136
	v_exp_f32_e32 v137, v137
	v_pk_add_f32 v[144:145], v[48:49], v[164:165]
	v_pk_add_f32 v[142:143], v[50:51], v[166:167]
	v_add_f32_e32 v136, 1.0, v136
	v_add_f32_e32 v137, 1.0, v137
	v_rcp_f32_e32 v136, v136
	v_rcp_f32_e32 v137, v137
	s_nop 0
	v_cvt_pk_bf16_f32 v136, v136, v137
	v_mul_f32_e32 v137, 0xbfb8aa3b, v138
	v_mul_f32_e32 v138, 0xbfb8aa3b, v139
	v_exp_f32_e32 v137, v137
	v_exp_f32_e32 v138, v138
	v_mul_f32_e32 v139, 0xbfb8aa3b, v145
	v_exp_f32_e32 v139, v139
	v_add_f32_e32 v137, 1.0, v137
	v_add_f32_e32 v138, 1.0, v138
	v_rcp_f32_e32 v137, v137
	v_rcp_f32_e32 v138, v138
	s_nop 0
	v_cvt_pk_bf16_f32 v137, v137, v138
	v_mul_f32_e32 v138, 0xbfb8aa3b, v144
	v_exp_f32_e32 v138, v138
	v_add_f32_e32 v139, 1.0, v139
	v_rcp_f32_e32 v139, v139
	v_pk_add_f32 v[144:145], v[32:33], v[164:165]
	v_add_f32_e32 v138, 1.0, v138
	v_rcp_f32_e32 v138, v138
	s_nop 0
	v_cvt_pk_bf16_f32 v138, v138, v139
	v_mul_f32_e32 v139, 0xbfb8aa3b, v142
	v_mul_f32_e32 v142, 0xbfb8aa3b, v143
	v_exp_f32_e32 v139, v139
	v_exp_f32_e32 v142, v142
	v_add_f32_e32 v139, 1.0, v139
	v_add_f32_e32 v142, 1.0, v142
	v_rcp_f32_e32 v139, v139
	v_rcp_f32_e32 v142, v142
	s_nop 0
	v_cvt_pk_bf16_f32 v139, v139, v142
	v_lshl_add_u64 v[142:143], v[148:149], 0, v[140:141]
	global_store_dwordx4 v[142:143], v[136:139], off
	v_pk_add_f32 v[142:143], v[34:35], v[166:167]
	s_nop 0
	v_pk_add_f32 v[136:137], v[36:37], v[168:169]
	v_pk_add_f32 v[138:139], v[38:39], v[170:171]
	v_mul_f32_e32 v136, 0xbfb8aa3b, v136
	v_mul_f32_e32 v137, 0xbfb8aa3b, v137
	v_exp_f32_e32 v136, v136
	v_exp_f32_e32 v137, v137
	v_add_f32_e32 v136, 1.0, v136
	v_add_f32_e32 v137, 1.0, v137
	v_rcp_f32_e32 v136, v136
	v_rcp_f32_e32 v137, v137
	s_nop 0
	v_cvt_pk_bf16_f32 v136, v136, v137
	v_mul_f32_e32 v137, 0xbfb8aa3b, v138
	v_mul_f32_e32 v138, 0xbfb8aa3b, v139
	v_exp_f32_e32 v137, v137
	v_exp_f32_e32 v138, v138
	v_mul_f32_e32 v139, 0xbfb8aa3b, v145
	v_exp_f32_e32 v139, v139
	v_add_f32_e32 v137, 1.0, v137
	v_add_f32_e32 v138, 1.0, v138
	v_rcp_f32_e32 v137, v137
	v_rcp_f32_e32 v138, v138
	s_nop 0
	v_cvt_pk_bf16_f32 v137, v137, v138
	v_mul_f32_e32 v138, 0xbfb8aa3b, v144
	v_exp_f32_e32 v138, v138
	v_add_f32_e32 v139, 1.0, v139
	v_rcp_f32_e32 v139, v139
	v_pk_add_f32 v[144:145], v[16:17], v[164:165]
	v_add_f32_e32 v138, 1.0, v138
	v_rcp_f32_e32 v138, v138
	s_nop 0
	v_cvt_pk_bf16_f32 v138, v138, v139
	v_mul_f32_e32 v139, 0xbfb8aa3b, v142
	v_mul_f32_e32 v142, 0xbfb8aa3b, v143
	v_exp_f32_e32 v139, v139
	v_exp_f32_e32 v142, v142
	v_add_f32_e32 v139, 1.0, v139
	v_add_f32_e32 v142, 1.0, v142
	v_rcp_f32_e32 v139, v139
	v_rcp_f32_e32 v142, v142
	s_nop 0
	v_cvt_pk_bf16_f32 v139, v139, v142
	v_lshl_add_u64 v[142:143], v[150:151], 0, v[140:141]
	global_store_dwordx4 v[142:143], v[136:139], off
	v_pk_add_f32 v[142:143], v[18:19], v[166:167]
	s_nop 0
	v_pk_add_f32 v[136:137], v[20:21], v[168:169]
	v_pk_add_f32 v[138:139], v[22:23], v[170:171]
	v_mul_f32_e32 v136, 0xbfb8aa3b, v136
	v_mul_f32_e32 v137, 0xbfb8aa3b, v137
	v_exp_f32_e32 v136, v136
	v_exp_f32_e32 v137, v137
	v_pk_add_f32 v[132:133], v[4:5], v[168:169]
	v_pk_add_f32 v[134:135], v[6:7], v[170:171]
	v_add_f32_e32 v136, 1.0, v136
	v_add_f32_e32 v137, 1.0, v137
	v_rcp_f32_e32 v136, v136
	v_rcp_f32_e32 v137, v137
	s_nop 0
	v_cvt_pk_bf16_f32 v136, v136, v137
	v_mul_f32_e32 v137, 0xbfb8aa3b, v138
	v_mul_f32_e32 v138, 0xbfb8aa3b, v139
	v_exp_f32_e32 v137, v137
	v_exp_f32_e32 v138, v138
	v_mul_f32_e32 v139, 0xbfb8aa3b, v145
	v_exp_f32_e32 v139, v139
	v_add_f32_e32 v137, 1.0, v137
	v_add_f32_e32 v138, 1.0, v138
	v_rcp_f32_e32 v137, v137
	v_rcp_f32_e32 v138, v138
	s_nop 0
	v_cvt_pk_bf16_f32 v137, v137, v138
	v_mul_f32_e32 v138, 0xbfb8aa3b, v144
	v_exp_f32_e32 v138, v138
	v_add_f32_e32 v139, 1.0, v139
	v_rcp_f32_e32 v139, v139
	v_add_f32_e32 v138, 1.0, v138
	v_rcp_f32_e32 v138, v138
	s_nop 0
	v_cvt_pk_bf16_f32 v138, v138, v139
	v_mul_f32_e32 v139, 0xbfb8aa3b, v142
	v_mul_f32_e32 v142, 0xbfb8aa3b, v143
	v_exp_f32_e32 v139, v139
	v_exp_f32_e32 v142, v142
	v_add_f32_e32 v139, 1.0, v139
	v_add_f32_e32 v142, 1.0, v142
	v_rcp_f32_e32 v139, v139
	v_rcp_f32_e32 v142, v142
	s_nop 0
	v_cvt_pk_bf16_f32 v139, v139, v142
	v_lshl_add_u64 v[142:143], v[152:153], 0, v[140:141]
	global_store_dwordx4 v[142:143], v[136:139], off
	s_nop 1
	v_pk_add_f32 v[136:137], v[2:3], v[166:167]
	v_pk_add_f32 v[130:131], v[0:1], v[164:165]
	v_mul_f32_e32 v128, 0xbfb8aa3b, v132
	v_mul_f32_e32 v129, 0xbfb8aa3b, v133
	v_exp_f32_e32 v128, v128
	v_exp_f32_e32 v129, v129
	v_mul_f32_e32 v132, 0xbfb8aa3b, v135
	v_mul_f32_e32 v130, 0xbfb8aa3b, v130
	v_add_f32_e32 v128, 1.0, v128
	v_add_f32_e32 v129, 1.0, v129
	v_rcp_f32_e32 v128, v128
	v_rcp_f32_e32 v129, v129
	s_nop 0
	v_cvt_pk_bf16_f32 v128, v128, v129
	v_mul_f32_e32 v129, 0xbfb8aa3b, v134
	v_mul_f32_e32 v131, 0xbfb8aa3b, v131
	v_exp_f32_e32 v129, v129
	v_exp_f32_e32 v132, v132
	v_exp_f32_e32 v130, v130
	v_exp_f32_e32 v131, v131
	v_add_f32_e32 v129, 1.0, v129
	v_add_f32_e32 v132, 1.0, v132
	v_add_f32_e32 v130, 1.0, v130
	v_add_f32_e32 v131, 1.0, v131
	v_rcp_f32_e32 v129, v129
	v_rcp_f32_e32 v132, v132
	v_rcp_f32_e32 v130, v130
	v_rcp_f32_e32 v131, v131
	s_nop 0
	v_cvt_pk_bf16_f32 v129, v129, v132
	v_cvt_pk_bf16_f32 v130, v130, v131
	v_mul_f32_e32 v131, 0xbfb8aa3b, v136
	v_mul_f32_e32 v132, 0xbfb8aa3b, v137
	v_exp_f32_e32 v131, v131
	v_exp_f32_e32 v132, v132
	v_add_f32_e32 v131, 1.0, v131
	v_add_f32_e32 v132, 1.0, v132
	v_rcp_f32_e32 v131, v131
	v_rcp_f32_e32 v132, v132
	s_nop 0
	v_cvt_pk_bf16_f32 v131, v131, v132
	v_lshl_add_u64 v[132:133], v[154:155], 0, v[140:141]
	global_store_dwordx4 v[132:133], v[128:131], off

; #define LAS __attribute__((address_space(3)))
; __device__ __forceinline__ void conv_fetch(const bf16_t* raw, int item, int tid, u32x4 (&rg)[3]) {
;     ...
;     for (int i = 0; i < 3; ++i) {
;         const int idx = tid + 512 * i;
;         rg[i] = (u32x4){0u, 0u, 0u, 0u};
;         if (idx < 134 * 8) { const int ir = idx >> 3, c8 = idx & 7; int tok; bool ok;
;             if (is_ctx) { tok = ir - 2; const int gt = (ch & 1) * 128 + tok; ok = (ir < 131) && gt >= 0 && gt < 256; }
;             else { const int sg = ir >= 67 ? 1 : 0, q = ir - 67 * sg; tok = 64 * sg + q - 2; ok = q >= 2 && q < 66; }
;             if (ok) rg[i] = *(const u32x4*)(raw + (size_t)(row0 + tok) * NA + fb * 64 + c8 * 8); }
; __device__ __forceinline__ void phase_conv(const Params& p, LAS unsigned char* lds, int wg, int G, int tid) {
;     ...
;         if (item + G < NIT) conv_fetch(raw, item + G, tid, rg);
;         const int ch = item / NFB, fb = item % NFB;
;         const size_t row0 = (size_t)ch * 128;
;         const int fp = tid & 31, tq = tid >> 5;
;         const int feat = fb * 64 + 2 * fp;
;         f32x2 w0, w1, w2, w3, bias;
;         if (feat < 4096) { w0 = *(const f32x2*)(p.ssd_conv_w + feat); w1 = *(const f32x2*)(p.ssd_conv_w + 4096 + feat); w2 = *(const f32x2*)(p.ssd_conv_w + 8192 + feat); w3 = *(const f32x2*)(p.ssd_conv_w + 12288 + feat); bias = *(const f32x2*)(p.ssd_conv_b + feat); }
;         else { const int lf = feat - 4096; w0 = *(const f32x2*)(p.lru_conv_w + lf); w1 = *(const f32x2*)(p.lru_conv_w + 1024 + lf); w2 = *(const f32x2*)(p.lru_conv_w + 2048 + lf); w3 = *(const f32x2*)(p.lru_conv_w + 3072 + lf); bias = *(const f32x2*)(p.lru_conv_b + lf); }
;         const bool is_ctx = ch < (CGR / 128);
;         const bool act = fb < 64;
;         f32x2 o[8];
;         const int ib0 = is_ctx ? tq * 8 : (tq >> 3) * 67 + (tq & 7) * 8;
;         const LAS f32x2* tp = (const LAS f32x2*)tile + fp;
;         f32x2 v0 = tp[(ib0 + 0) * 32], v1 = tp[(ib0 + 1) * 32], v2 = tp[(ib0 + 2) * 32];
; #pragma unroll
;         for (int k = 0; k < 8; ++k) {
;             const f32x2 v3 = tp[(ib0 + k + 3) * 32];
;             f32x2 a = bias + w0 * v0 + w1 * v1 + w2 * v2 + w3 * v3;
.LBB0_650:
	s_or_b64 exec, exec, s[20:21]
	global_load_dwordx2 v[30:31], v[12:13], off
	global_load_dwordx2 v[32:33], v[28:29], off
	global_load_dwordx2 v[38:39], v[14:15], off
	global_load_dwordx2 v[36:37], v[16:17], off
	global_load_dwordx2 v[34:35], v[18:19], off
	s_mul_i32 s20, s48, 0xffffffb0
	s_add_i32 s45, s41, s20
	s_cmpk_lt_i32 s41, 0xa00
	s_cselect_b64 s[20:21], -1, 0
	v_cndmask_b32_e64 v12, v59, v22, s[20:21]
	v_lshl_add_u32 v13, v57, 3, s44
	v_lshlrev_b32_e32 v12, 8, v12
	v_add_u32_e32 v27, v13, v12
	ds_read2_b64 v[16:19], v27 offset1:32
	ds_read2_b64 v[12:15], v27 offset0:64 offset1:96
	s_cmp_lt_i32 s45, 64
	s_cselect_b64 s[50:51], -1, 0
	s_cmp_gt_i32 s45, 63
	s_waitcnt vmcnt(3) lgkmcnt(1)
	v_pk_fma_f32 v[16:17], v[30:31], v[16:17], v[32:33]
	s_waitcnt vmcnt(2)
	v_pk_fma_f32 v[16:17], v[38:39], v[18:19], v[16:17]
	s_waitcnt vmcnt(1) lgkmcnt(0)
	v_pk_fma_f32 v[16:17], v[36:37], v[12:13], v[16:17]
	s_waitcnt vmcnt(0)
	v_pk_fma_f32 v[16:17], v[34:35], v[14:15], v[16:17]
	v_mov_b32_e32 v0, v68
	v_mov_b32_e32 v1, v69
	v_mov_b32_e32 v2, v70
	v_mov_b32_e32 v3, v71
	v_mov_b32_e32 v4, v72
	v_mov_b32_e32 v5, v73
	v_mov_b32_e32 v6, v74
	v_mov_b32_e32 v7, v75
	v_mov_b32_e32 v8, v76
	v_mov_b32_e32 v9, v77
	v_mov_b32_e32 v10, v78
	v_mov_b32_e32 v11, v79
	s_mov_b32 s101, s45
	v_writelane_b32 v255, s48, 63
	v_writelane_b32 v255, s50, 59
	v_writelane_b32 v255, s51, 60
	s_add_i32 s100, s40, s34
	s_cmpk_gt_i32 s100, 0x59ff
	s_cbranch_scc1 .Lconv_nopf
	s_mul_hi_i32 s20, s100, 0x66666667
	s_lshr_b32 s21, s20, 31
	s_ashr_i32 s20, s20, 5
	s_add_i32 s20, s20, s21
	s_cmpk_lt_i32 s100, 0xa00
	s_cselect_b64 vcc, -1, 0
	s_ashr_i32 s21, s20, 31
	s_lshl_b64 s[22:23], s[20:21], 7
	s_lshl_b32 s21, s20, 7
	s_and_b32 s45, s21, 0x80
	s_mulk_i32 s20, 0xec00
	s_add_i32 s21, s39, s38
	s_add_i32 s21, s21, s39
	s_add_i32 s20, s21, s20
	s_ashr_i32 s21, s20, 31
	v_lshl_add_u64 v[66:67], s[20:21], 1, v[20:21]
	v_mov_b32_e32 v72, 0
	v_mov_b32_e32 v68, 0
	v_mov_b32_e32 v69, 0
	v_mov_b32_e32 v70, 0
	v_mov_b32_e32 v71, 0
	s_and_saveexec_b64 s[48:49], s[2:3]
	s_cbranch_execz .Lconv_l_637
	v_add_u32_e32 v68, s45, v51
	s_movk_i32 s20, 0x100
	v_cmp_gt_u32_e64 s[20:21], s20, v68
	s_and_b64 s[20:21], s[6:7], s[20:21]
	v_cndmask_b32_e64 v69, 0, 1, s[4:5]
	v_cndmask_b32_e64 v68, 0, 1, s[20:21]
	v_cndmask_b32_e32 v68, v69, v68, vcc
	v_and_b32_e32 v68, 1, v68
	v_cmp_eq_u32_e64 s[20:21], 1, v68
	v_mov_b32_e32 v71, 0
	v_mov_b32_e32 v70, 0
	v_mov_b32_e32 v69, 0
	v_mov_b32_e32 v68, 0
	s_and_saveexec_b64 s[50:51], s[20:21]
	s_cbranch_execz .Lconv_l_636
	v_cndmask_b32_e32 v68, v52, v51, vcc
	v_ashrrev_i32_e32 v69, 31, v68
	v_lshl_add_u64 v[68:69], s[22:23], 0, v[68:69]
	v_mad_u64_u32 v[70:71], s[20:21], v68, s78, v[66:67]
	v_mad_i32_i24 v71, v69, s78, v71
	global_load_dwordx4 v[68:71], v[70:71], off

; __device__ __forceinline__ void conv_fetch(const bf16_t* raw, int item, int tid, u32x4 (&rg)[3]) {
;     ...
;         if (idx < 134 * 8) { const int ir = idx >> 3, c8 = idx & 7; int tok; bool ok;
;             if (is_ctx) { tok = ir - 2; const int gt = (ch & 1) * 128 + tok; ok = (ir < 131) && gt >= 0 && gt < 256; }
;             else { const int sg = ir >= 67 ? 1 : 0, q = ir - 67 * sg; tok = 64 * sg + q - 2; ok = q >= 2 && q < 66; }
;             if (ok) rg[i] = *(const u32x4*)(raw + (size_t)(row0 + tok) * NA + fb * 64 + c8 * 8); }
; __device__ __forceinline__ void phase_conv(const Params& p, LAS unsigned char* lds, int wg, int G, int tid) {
;     ...
;             if (act) { f32x2 d; d.x = 1.f + __expf(-a.x); d.y = 1.f + __expf(-a.y); f32x2 rc; rc.x = __builtin_amdgcn_rcpf(d.x); rc.y = __builtin_amdgcn_rcpf(d.y); a = a * rc; }
;             o[k] = a;
;             v0 = v1; v1 = v2; v2 = v3;
;         }
.Lconv_nopf:
	v_readlane_b32 s50, v255, 59
	v_readlane_b32 s51, v255, 60
	s_cmpk_lt_i32 s41, 0xa00
	s_cselect_b64 s[20:21], -1, 0
	v_readlane_b32 s48, v255, 63
	s_mov_b32 s45, s101
	s_nop 3
	s_cmp_gt_i32 s45, 63
	s_cbranch_scc1 .LBB0_652
	v_mul_f32_e32 v28, 0xbfb8aa3b, v16
	v_mul_f32_e32 v29, 0xbfb8aa3b, v17
	v_exp_f32_e32 v28, v28
	v_exp_f32_e32 v29, v29
	v_add_f32_e32 v28, 1.0, v28
	v_add_f32_e32 v29, 1.0, v29
	v_rcp_f32_e32 v28, v28
	v_rcp_f32_e32 v29, v29
	s_nop 0
	v_pk_mul_f32 v[16:17], v[16:17], v[28:29]
